# per-phase s_setprio flips deleted from the five GEMM K-loops (on top of attention back-edge rotation, address precompute and P11 pipelining)
# speedup vs baseline: 1.0022x; 1.0019x over previous
.LBB0_366:
	ds_read_b128 v[128:131], v172
	ds_read_b128 v[132:135], v172 offset:1024
	ds_read_b128 v[136:139], v172 offset:2048
	ds_read_b128 v[140:143], v172 offset:3072
	ds_read_b128 v[166:169], v173
	ds_read_b128 v[180:183], v173 offset:1024
	ds_read_b128 v[184:187], v173 offset:2048
	ds_read_b128 v[188:191], v173 offset:3072
	s_add_u32 s26, s42, 0xfffc0080
	s_addc_u32 s27, s43, -1
	s_cmp_eq_u32 s76, 12
	s_cselect_b32 s51, s7, s27
	s_cselect_b32 s50, s25, s26
	s_cselect_b32 s45, s23, s75
	s_cselect_b32 s44, s73, s74
	v_lshl_add_u64 v[224:225], s[42:43], 0, v[158:159]
	s_add_i32 m0, s41, 0xc000
	ds_read_b128 v[192:195], v174
	ds_read_b128 v[196:199], v174 offset:1024
	ds_read_b128 v[200:203], v174 offset:2048
	ds_read_b128 v[204:207], v174 offset:3072
	ds_read_b128 v[208:211], v174 offset:4096
	ds_read_b128 v[212:215], v174 offset:5120
	ds_read_b128 v[216:219], v174 offset:6144
	ds_read_b128 v[220:223], v174 offset:7168
	global_load_lds_dwordx4 v[224:225], off
	v_lshl_add_u64 v[224:225], s[42:43], 0, v[160:161]
	s_add_i32 m0, s41, 0xe000
	s_nop 0
	global_load_lds_dwordx4 v[224:225], off
	s_waitcnt vmcnt(8)
	s_waitcnt lgkmcnt(0)
	s_barrier
	s_waitcnt lgkmcnt(0)
	v_mfma_f32_16x16x32_bf16 v[124:127], v[128:131], v[192:195], v[124:127]
	v_mfma_f32_16x16x32_bf16 v[120:123], v[136:139], v[192:195], v[120:123]
	v_mfma_f32_16x16x32_bf16 v[108:111], v[128:131], v[200:203], v[108:111]
	v_mfma_f32_16x16x32_bf16 v[104:107], v[136:139], v[200:203], v[104:107]
	v_mfma_f32_16x16x32_bf16 v[92:95], v[128:131], v[208:211], v[92:95]
	v_mfma_f32_16x16x32_bf16 v[88:91], v[136:139], v[208:211], v[88:91]
	v_mfma_f32_16x16x32_bf16 v[76:79], v[128:131], v[216:219], v[76:79]
	v_mfma_f32_16x16x32_bf16 v[72:75], v[136:139], v[216:219], v[72:75]
	v_mfma_f32_16x16x32_bf16 v[124:127], v[132:135], v[196:199], v[124:127]
	v_mfma_f32_16x16x32_bf16 v[120:123], v[140:143], v[196:199], v[120:123]
	v_mfma_f32_16x16x32_bf16 v[108:111], v[132:135], v[204:207], v[108:111]
	v_mfma_f32_16x16x32_bf16 v[104:107], v[140:143], v[204:207], v[104:107]
	v_mfma_f32_16x16x32_bf16 v[92:95], v[132:135], v[212:215], v[92:95]
	v_mfma_f32_16x16x32_bf16 v[88:91], v[140:143], v[212:215], v[88:91]
	v_mfma_f32_16x16x32_bf16 v[76:79], v[132:135], v[220:223], v[76:79]
	v_mfma_f32_16x16x32_bf16 v[72:75], v[140:143], v[220:223], v[72:75]
	v_mfma_f32_16x16x32_bf16 v[116:119], v[166:169], v[192:195], v[116:119]
	v_mfma_f32_16x16x32_bf16 v[112:115], v[184:187], v[192:195], v[112:115]
	v_mfma_f32_16x16x32_bf16 v[100:103], v[166:169], v[200:203], v[100:103]
	v_mfma_f32_16x16x32_bf16 v[96:99], v[184:187], v[200:203], v[96:99]
	v_mfma_f32_16x16x32_bf16 v[84:87], v[166:169], v[208:211], v[84:87]
	v_mfma_f32_16x16x32_bf16 v[80:83], v[184:187], v[208:211], v[80:83]
	v_mfma_f32_16x16x32_bf16 v[68:71], v[166:169], v[216:219], v[68:71]
	v_mfma_f32_16x16x32_bf16 v[64:67], v[184:187], v[216:219], v[64:67]
	v_mfma_f32_16x16x32_bf16 v[116:119], v[180:183], v[196:199], v[116:119]
	v_mfma_f32_16x16x32_bf16 v[112:115], v[188:191], v[196:199], v[112:115]
	v_mfma_f32_16x16x32_bf16 v[100:103], v[180:183], v[204:207], v[100:103]
	v_mfma_f32_16x16x32_bf16 v[96:99], v[188:191], v[204:207], v[96:99]
	v_mfma_f32_16x16x32_bf16 v[84:87], v[180:183], v[212:215], v[84:87]
	v_mfma_f32_16x16x32_bf16 v[80:83], v[188:191], v[212:215], v[80:83]
	v_mfma_f32_16x16x32_bf16 v[68:71], v[180:183], v[220:223], v[68:71]
	v_mfma_f32_16x16x32_bf16 v[64:67], v[188:191], v[220:223], v[64:67]
	s_barrier
	s_add_i32 s26, s65, s52
	v_lshl_add_u64 v[224:225], s[44:45], 0, v[146:147]
	s_mov_b32 m0, s26
	ds_read_b128 v[192:195], v174 offset:16384
	ds_read_b128 v[196:199], v174 offset:17408
	ds_read_b128 v[200:203], v174 offset:18432
	ds_read_b128 v[204:207], v174 offset:19456
	ds_read_b128 v[208:211], v174 offset:20480
	ds_read_b128 v[212:215], v174 offset:21504
	ds_read_b128 v[216:219], v174 offset:22528
	ds_read_b128 v[220:223], v174 offset:23552
	global_load_lds_dwordx4 v[224:225], off
	s_add_i32 m0, s26, 0x2000
	s_add_u32 s26, s44, 0x40000
	v_lshl_add_u64 v[226:227], s[44:45], 0, v[150:151]
	s_addc_u32 s27, s45, 0
	s_add_i32 s54, s67, s52
	global_load_lds_dwordx4 v[226:227], off
	v_lshl_add_u64 v[228:229], s[26:27], 0, v[146:147]
	s_mov_b32 m0, s54
	v_lshl_add_u64 v[230:231], s[50:51], 0, v[148:149]
	global_load_lds_dwordx4 v[228:229], off
	v_lshl_add_u64 v[228:229], s[26:27], 0, v[150:151]
	s_add_i32 m0, s54, 0x2000
	s_nop 0
	global_load_lds_dwordx4 v[228:229], off
	v_lshl_add_u64 v[228:229], s[50:51], 0, v[144:145]
	s_mov_b32 m0, s41
	s_nop 0
	global_load_lds_dwordx4 v[228:229], off
	s_mov_b32 m0, s53
	s_nop 0
	global_load_lds_dwordx4 v[230:231], off
	s_waitcnt vmcnt(8)
	s_waitcnt lgkmcnt(0)
	s_barrier
	s_waitcnt lgkmcnt(0)
	v_mfma_f32_16x16x32_bf16 v[60:63], v[128:131], v[192:195], v[60:63]
	v_mfma_f32_16x16x32_bf16 v[56:59], v[136:139], v[192:195], v[56:59]
	v_mfma_f32_16x16x32_bf16 v[44:47], v[128:131], v[200:203], v[44:47]
	v_mfma_f32_16x16x32_bf16 v[40:43], v[136:139], v[200:203], v[40:43]
	v_mfma_f32_16x16x32_bf16 v[28:31], v[128:131], v[208:211], v[28:31]
	v_mfma_f32_16x16x32_bf16 v[24:27], v[136:139], v[208:211], v[24:27]
	v_mfma_f32_16x16x32_bf16 v[12:15], v[128:131], v[216:219], v[12:15]
	v_mfma_f32_16x16x32_bf16 v[8:11], v[136:139], v[216:219], v[8:11]
	v_mfma_f32_16x16x32_bf16 v[60:63], v[132:135], v[196:199], v[60:63]
	v_mfma_f32_16x16x32_bf16 v[56:59], v[140:143], v[196:199], v[56:59]
	v_mfma_f32_16x16x32_bf16 v[44:47], v[132:135], v[204:207], v[44:47]
	v_mfma_f32_16x16x32_bf16 v[40:43], v[140:143], v[204:207], v[40:43]
	v_mfma_f32_16x16x32_bf16 v[28:31], v[132:135], v[212:215], v[28:31]
	v_mfma_f32_16x16x32_bf16 v[24:27], v[140:143], v[212:215], v[24:27]
	v_mfma_f32_16x16x32_bf16 v[12:15], v[132:135], v[220:223], v[12:15]
	v_mfma_f32_16x16x32_bf16 v[8:11], v[140:143], v[220:223], v[8:11]
	v_mfma_f32_16x16x32_bf16 v[52:55], v[166:169], v[192:195], v[52:55]
	v_mfma_f32_16x16x32_bf16 v[48:51], v[184:187], v[192:195], v[48:51]
	v_mfma_f32_16x16x32_bf16 v[36:39], v[166:169], v[200:203], v[36:39]
	v_mfma_f32_16x16x32_bf16 v[32:35], v[184:187], v[200:203], v[32:35]
	v_mfma_f32_16x16x32_bf16 v[20:23], v[166:169], v[208:211], v[20:23]
	v_mfma_f32_16x16x32_bf16 v[16:19], v[184:187], v[208:211], v[16:19]
	v_mfma_f32_16x16x32_bf16 v[4:7], v[166:169], v[216:219], v[4:7]
	v_mfma_f32_16x16x32_bf16 v[0:3], v[184:187], v[216:219], v[0:3]
	v_mfma_f32_16x16x32_bf16 v[52:55], v[180:183], v[196:199], v[52:55]
	v_mfma_f32_16x16x32_bf16 v[48:51], v[188:191], v[196:199], v[48:51]
	v_mfma_f32_16x16x32_bf16 v[36:39], v[180:183], v[204:207], v[36:39]
	v_mfma_f32_16x16x32_bf16 v[32:35], v[188:191], v[204:207], v[32:35]
	v_mfma_f32_16x16x32_bf16 v[20:23], v[180:183], v[212:215], v[20:23]
	v_mfma_f32_16x16x32_bf16 v[16:19], v[188:191], v[212:215], v[16:19]
	v_mfma_f32_16x16x32_bf16 v[4:7], v[180:183], v[220:223], v[4:7]
	v_mfma_f32_16x16x32_bf16 v[0:3], v[188:191], v[220:223], v[0:3]
	s_barrier
	s_add_i32 s54, 0, 0x18000
	s_add_i32 s55, 0, 0x1c000
	v_add_u32_e32 v140, s54, v170
	v_add_u32_e32 v152, s55, v170
	ds_read_b128 v[128:131], v140
	ds_read_b128 v[132:135], v140 offset:1024
	ds_read_b128 v[136:139], v140 offset:2048
	ds_read_b128 v[140:143], v140 offset:3072
	ds_read_b128 v[166:169], v152
	ds_read_b128 v[180:183], v152 offset:1024
	ds_read_b128 v[184:187], v152 offset:2048
	ds_read_b128 v[188:191], v152 offset:3072
	s_add_u32 s26, s50, 0x40000
	s_addc_u32 s27, s51, 0
	s_mov_b32 m0, s56
	v_lshl_add_u64 v[232:233], s[26:27], 0, v[144:145]
	ds_read_b128 v[192:195], v174 offset:32768
	ds_read_b128 v[196:199], v174 offset:33792
	ds_read_b128 v[200:203], v174 offset:34816
	ds_read_b128 v[204:207], v174 offset:35840
	ds_read_b128 v[208:211], v174 offset:36864
	ds_read_b128 v[212:215], v174 offset:37888
	ds_read_b128 v[216:219], v174 offset:38912
	ds_read_b128 v[220:223], v174 offset:39936
	global_load_lds_dwordx4 v[232:233], off
	v_lshl_add_u64 v[232:233], s[26:27], 0, v[148:149]
	s_mov_b32 m0, s57
	s_nop 0
	global_load_lds_dwordx4 v[232:233], off
	s_waitcnt vmcnt(8)
	s_waitcnt lgkmcnt(0)
	s_barrier
	s_waitcnt lgkmcnt(0)
	v_mfma_f32_16x16x32_bf16 v[124:127], v[128:131], v[192:195], v[124:127]
	v_mfma_f32_16x16x32_bf16 v[120:123], v[136:139], v[192:195], v[120:123]
	v_mfma_f32_16x16x32_bf16 v[108:111], v[128:131], v[200:203], v[108:111]
	v_mfma_f32_16x16x32_bf16 v[104:107], v[136:139], v[200:203], v[104:107]
	v_mfma_f32_16x16x32_bf16 v[92:95], v[128:131], v[208:211], v[92:95]
	v_mfma_f32_16x16x32_bf16 v[88:91], v[136:139], v[208:211], v[88:91]
	v_mfma_f32_16x16x32_bf16 v[76:79], v[128:131], v[216:219], v[76:79]
	v_mfma_f32_16x16x32_bf16 v[72:75], v[136:139], v[216:219], v[72:75]
	v_mfma_f32_16x16x32_bf16 v[124:127], v[132:135], v[196:199], v[124:127]
	v_mfma_f32_16x16x32_bf16 v[120:123], v[140:143], v[196:199], v[120:123]
	v_mfma_f32_16x16x32_bf16 v[108:111], v[132:135], v[204:207], v[108:111]
	v_mfma_f32_16x16x32_bf16 v[104:107], v[140:143], v[204:207], v[104:107]
	v_mfma_f32_16x16x32_bf16 v[92:95], v[132:135], v[212:215], v[92:95]
	v_mfma_f32_16x16x32_bf16 v[88:91], v[140:143], v[212:215], v[88:91]
	v_mfma_f32_16x16x32_bf16 v[76:79], v[132:135], v[220:223], v[76:79]
	v_mfma_f32_16x16x32_bf16 v[72:75], v[140:143], v[220:223], v[72:75]
	v_mfma_f32_16x16x32_bf16 v[116:119], v[166:169], v[192:195], v[116:119]
	v_mfma_f32_16x16x32_bf16 v[112:115], v[184:187], v[192:195], v[112:115]
	v_mfma_f32_16x16x32_bf16 v[100:103], v[166:169], v[200:203], v[100:103]
	v_mfma_f32_16x16x32_bf16 v[96:99], v[184:187], v[200:203], v[96:99]
	v_mfma_f32_16x16x32_bf16 v[84:87], v[166:169], v[208:211], v[84:87]
	v_mfma_f32_16x16x32_bf16 v[80:83], v[184:187], v[208:211], v[80:83]
	v_mfma_f32_16x16x32_bf16 v[68:71], v[166:169], v[216:219], v[68:71]
	v_mfma_f32_16x16x32_bf16 v[64:67], v[184:187], v[216:219], v[64:67]
	v_mfma_f32_16x16x32_bf16 v[116:119], v[180:183], v[196:199], v[116:119]
	v_mfma_f32_16x16x32_bf16 v[112:115], v[188:191], v[196:199], v[112:115]
	v_mfma_f32_16x16x32_bf16 v[100:103], v[180:183], v[204:207], v[100:103]
	v_mfma_f32_16x16x32_bf16 v[96:99], v[188:191], v[204:207], v[96:99]
	v_mfma_f32_16x16x32_bf16 v[84:87], v[180:183], v[212:215], v[84:87]
	v_mfma_f32_16x16x32_bf16 v[80:83], v[188:191], v[212:215], v[80:83]
	v_mfma_f32_16x16x32_bf16 v[68:71], v[180:183], v[220:223], v[68:71]
	v_mfma_f32_16x16x32_bf16 v[64:67], v[188:191], v[220:223], v[64:67]
	s_barrier
	s_add_i32 s26, s54, s52
	v_lshl_add_u64 v[224:225], v[224:225], 0, s[8:9]
	s_mov_b32 m0, s26
	ds_read_b128 v[192:195], v174 offset:49152
	ds_read_b128 v[196:199], v174 offset:50176
	ds_read_b128 v[200:203], v174 offset:51200
	ds_read_b128 v[204:207], v174 offset:52224
	ds_read_b128 v[208:211], v174 offset:53248
	ds_read_b128 v[212:215], v174 offset:54272
	ds_read_b128 v[216:219], v174 offset:55296
	ds_read_b128 v[220:223], v174 offset:56320
	global_load_lds_dwordx4 v[224:225], off
	s_add_i32 m0, s26, 0x2000
	s_add_u32 s26, s44, 0x40080
	v_lshl_add_u64 v[224:225], v[226:227], 0, s[8:9]
	s_addc_u32 s27, s45, 0
	s_add_i32 s44, s55, s52
	global_load_lds_dwordx4 v[224:225], off
	v_lshl_add_u64 v[224:225], s[26:27], 0, v[146:147]
	s_mov_b32 m0, s44
	s_nop 0
	global_load_lds_dwordx4 v[224:225], off
	v_lshl_add_u64 v[224:225], s[26:27], 0, v[150:151]
	s_add_i32 m0, s44, 0x2000
	s_nop 0
	global_load_lds_dwordx4 v[224:225], off
	v_lshl_add_u64 v[224:225], v[228:229], 0, s[8:9]
	s_mov_b32 m0, s60
	s_nop 0
	global_load_lds_dwordx4 v[224:225], off
	v_lshl_add_u64 v[224:225], v[230:231], 0, s[8:9]
	s_mov_b32 m0, s61
	s_nop 0
	global_load_lds_dwordx4 v[224:225], off
	s_waitcnt vmcnt(8)
	s_waitcnt lgkmcnt(0)
	s_barrier
	s_waitcnt lgkmcnt(0)
	v_mfma_f32_16x16x32_bf16 v[60:63], v[128:131], v[192:195], v[60:63]
	v_mfma_f32_16x16x32_bf16 v[56:59], v[136:139], v[192:195], v[56:59]
	v_mfma_f32_16x16x32_bf16 v[44:47], v[128:131], v[200:203], v[44:47]
	v_mfma_f32_16x16x32_bf16 v[40:43], v[136:139], v[200:203], v[40:43]
	v_mfma_f32_16x16x32_bf16 v[28:31], v[128:131], v[208:211], v[28:31]
	v_mfma_f32_16x16x32_bf16 v[24:27], v[136:139], v[208:211], v[24:27]
	v_mfma_f32_16x16x32_bf16 v[12:15], v[128:131], v[216:219], v[12:15]
	v_mfma_f32_16x16x32_bf16 v[8:11], v[136:139], v[216:219], v[8:11]
	v_mfma_f32_16x16x32_bf16 v[60:63], v[132:135], v[196:199], v[60:63]
	v_mfma_f32_16x16x32_bf16 v[56:59], v[140:143], v[196:199], v[56:59]
	v_mfma_f32_16x16x32_bf16 v[44:47], v[132:135], v[204:207], v[44:47]
	v_mfma_f32_16x16x32_bf16 v[40:43], v[140:143], v[204:207], v[40:43]
	v_mfma_f32_16x16x32_bf16 v[28:31], v[132:135], v[212:215], v[28:31]
	v_mfma_f32_16x16x32_bf16 v[24:27], v[140:143], v[212:215], v[24:27]
	v_mfma_f32_16x16x32_bf16 v[12:15], v[132:135], v[220:223], v[12:15]
	v_mfma_f32_16x16x32_bf16 v[8:11], v[140:143], v[220:223], v[8:11]
	v_mfma_f32_16x16x32_bf16 v[52:55], v[166:169], v[192:195], v[52:55]
	v_mfma_f32_16x16x32_bf16 v[48:51], v[184:187], v[192:195], v[48:51]
	v_mfma_f32_16x16x32_bf16 v[36:39], v[166:169], v[200:203], v[36:39]
	v_mfma_f32_16x16x32_bf16 v[32:35], v[184:187], v[200:203], v[32:35]
	v_mfma_f32_16x16x32_bf16 v[20:23], v[166:169], v[208:211], v[20:23]
	v_mfma_f32_16x16x32_bf16 v[16:19], v[184:187], v[208:211], v[16:19]
	v_mfma_f32_16x16x32_bf16 v[4:7], v[166:169], v[216:219], v[4:7]
	v_mfma_f32_16x16x32_bf16 v[0:3], v[184:187], v[216:219], v[0:3]
	v_mfma_f32_16x16x32_bf16 v[52:55], v[180:183], v[196:199], v[52:55]
	v_mfma_f32_16x16x32_bf16 v[48:51], v[188:191], v[196:199], v[48:51]
	v_mfma_f32_16x16x32_bf16 v[36:39], v[180:183], v[204:207], v[36:39]
	v_mfma_f32_16x16x32_bf16 v[32:35], v[188:191], v[204:207], v[32:35]
	v_mfma_f32_16x16x32_bf16 v[20:23], v[180:183], v[212:215], v[20:23]
	v_mfma_f32_16x16x32_bf16 v[16:19], v[188:191], v[212:215], v[16:19]
	v_mfma_f32_16x16x32_bf16 v[4:7], v[180:183], v[220:223], v[4:7]
	v_mfma_f32_16x16x32_bf16 v[0:3], v[188:191], v[220:223], v[0:3]
	s_barrier
	s_add_i32 s76, s76, 2
	s_add_u32 s42, s42, 0x100
	s_addc_u32 s43, s43, 0
	s_add_u32 s74, s74, 0x100
	s_addc_u32 s75, s75, 0
	s_cmp_gt_u32 s76, 13
	s_cbranch_scc0 .LBB0_366
	s_and_b64 vcc, exec, s[10:11]
	s_cbranch_vccz .LBB0_369
	s_barrier

.LBB0_635:
	ds_read_b128 v[56:59], v176
	ds_read_b128 v[60:63], v176 offset:1024
	ds_read_b128 v[64:67], v176 offset:2048
	ds_read_b128 v[68:71], v176 offset:3072
	ds_read_b128 v[164:167], v177
	ds_read_b128 v[168:171], v177 offset:1024
	ds_read_b128 v[180:183], v177 offset:2048
	ds_read_b128 v[184:187], v177 offset:3072
	s_add_u32 s26, s52, 0x3ff000
	s_addc_u32 s27, s53, 0
	s_cmp_eq_u32 s80, 4
	s_cselect_b32 s60, s51, s26
	s_cselect_b32 s61, s41, s27
	s_cselect_b32 s58, s75, s76
	s_cselect_b32 s59, s39, s77
	s_add_u32 s56, s60, 0x400000
	s_addc_u32 s57, s61, 0
	v_lshl_add_u64 v[172:173], s[52:53], 0, v[156:157]
	s_add_i32 m0, s62, 0xc000
	ds_read_b128 v[188:191], v178
	ds_read_b128 v[192:195], v178 offset:1024
	ds_read_b128 v[196:199], v178 offset:2048
	ds_read_b128 v[200:203], v178 offset:3072
	ds_read_b128 v[204:207], v178 offset:4096
	ds_read_b128 v[208:211], v178 offset:5120
	ds_read_b128 v[212:215], v178 offset:6144
	ds_read_b128 v[216:219], v178 offset:7168
	global_load_lds_dwordx4 v[172:173], off
	v_lshl_add_u64 v[172:173], s[52:53], 0, v[158:159]
	s_add_i32 m0, s62, 0xe000
	s_nop 0
	global_load_lds_dwordx4 v[172:173], off
	s_waitcnt vmcnt(8)
	s_waitcnt lgkmcnt(0)
	s_barrier
	s_waitcnt lgkmcnt(0)
	v_mfma_f32_16x16x32_bf16 v[140:143], v[56:59], v[188:191], v[140:143]
	v_mfma_f32_16x16x32_bf16 v[136:139], v[64:67], v[188:191], v[136:139]
	v_mfma_f32_16x16x32_bf16 v[124:127], v[56:59], v[196:199], v[124:127]
	v_mfma_f32_16x16x32_bf16 v[120:123], v[64:67], v[196:199], v[120:123]
	v_mfma_f32_16x16x32_bf16 v[108:111], v[56:59], v[204:207], v[108:111]
	v_mfma_f32_16x16x32_bf16 v[104:107], v[64:67], v[204:207], v[104:107]
	v_mfma_f32_16x16x32_bf16 v[92:95], v[56:59], v[212:215], v[92:95]
	v_mfma_f32_16x16x32_bf16 v[88:91], v[64:67], v[212:215], v[88:91]
	v_mfma_f32_16x16x32_bf16 v[140:143], v[60:63], v[192:195], v[140:143]
	v_mfma_f32_16x16x32_bf16 v[136:139], v[68:71], v[192:195], v[136:139]
	v_mfma_f32_16x16x32_bf16 v[124:127], v[60:63], v[200:203], v[124:127]
	v_mfma_f32_16x16x32_bf16 v[120:123], v[68:71], v[200:203], v[120:123]
	v_mfma_f32_16x16x32_bf16 v[108:111], v[60:63], v[208:211], v[108:111]
	v_mfma_f32_16x16x32_bf16 v[104:107], v[68:71], v[208:211], v[104:107]
	v_mfma_f32_16x16x32_bf16 v[92:95], v[60:63], v[216:219], v[92:95]
	v_mfma_f32_16x16x32_bf16 v[88:91], v[68:71], v[216:219], v[88:91]
	v_mfma_f32_16x16x32_bf16 v[132:135], v[164:167], v[188:191], v[132:135]
	v_mfma_f32_16x16x32_bf16 v[128:131], v[180:183], v[188:191], v[128:131]
	v_mfma_f32_16x16x32_bf16 v[116:119], v[164:167], v[196:199], v[116:119]
	v_mfma_f32_16x16x32_bf16 v[112:115], v[180:183], v[196:199], v[112:115]
	v_mfma_f32_16x16x32_bf16 v[100:103], v[164:167], v[204:207], v[100:103]
	v_mfma_f32_16x16x32_bf16 v[96:99], v[180:183], v[204:207], v[96:99]
	v_mfma_f32_16x16x32_bf16 v[84:87], v[164:167], v[212:215], v[84:87]
	v_mfma_f32_16x16x32_bf16 v[80:83], v[180:183], v[212:215], v[80:83]
	v_mfma_f32_16x16x32_bf16 v[132:135], v[168:171], v[192:195], v[132:135]
	v_mfma_f32_16x16x32_bf16 v[128:131], v[184:187], v[192:195], v[128:131]
	v_mfma_f32_16x16x32_bf16 v[116:119], v[168:171], v[200:203], v[116:119]
	v_mfma_f32_16x16x32_bf16 v[112:115], v[184:187], v[200:203], v[112:115]
	v_mfma_f32_16x16x32_bf16 v[100:103], v[168:171], v[208:211], v[100:103]
	v_mfma_f32_16x16x32_bf16 v[96:99], v[184:187], v[208:211], v[96:99]
	v_mfma_f32_16x16x32_bf16 v[84:87], v[168:171], v[216:219], v[84:87]
	v_mfma_f32_16x16x32_bf16 v[80:83], v[184:187], v[216:219], v[80:83]
	s_barrier
	s_add_i32 s26, s72, s3
	v_lshl_add_u64 v[172:173], s[58:59], 0, v[146:147]
	s_mov_b32 m0, s26
	ds_read_b128 v[188:191], v178 offset:16384
	ds_read_b128 v[192:195], v178 offset:17408
	ds_read_b128 v[196:199], v178 offset:18432
	ds_read_b128 v[200:203], v178 offset:19456
	ds_read_b128 v[204:207], v178 offset:20480
	ds_read_b128 v[208:211], v178 offset:21504
	ds_read_b128 v[212:215], v178 offset:22528
	ds_read_b128 v[216:219], v178 offset:23552
	global_load_lds_dwordx4 v[172:173], off
	s_add_i32 m0, s26, 0x2000
	s_add_u32 s26, s58, 0x20000
	v_lshl_add_u64 v[220:221], s[58:59], 0, v[150:151]
	s_addc_u32 s27, s59, 0
	s_add_i32 s54, s73, s3
	global_load_lds_dwordx4 v[220:221], off
	v_lshl_add_u64 v[222:223], s[26:27], 0, v[146:147]
	s_mov_b32 m0, s54
	s_nop 0
	global_load_lds_dwordx4 v[222:223], off
	v_lshl_add_u64 v[222:223], s[26:27], 0, v[150:151]
	s_add_i32 m0, s54, 0x2000
	s_nop 0
	global_load_lds_dwordx4 v[222:223], off
	v_lshl_add_u64 v[222:223], s[60:61], 0, v[144:145]
	s_mov_b32 m0, s62
	s_nop 0
	global_load_lds_dwordx4 v[222:223], off
	v_lshl_add_u64 v[222:223], s[60:61], 0, v[148:149]
	s_mov_b32 m0, s63
	s_nop 0
	global_load_lds_dwordx4 v[222:223], off
	s_waitcnt vmcnt(8)
	s_waitcnt lgkmcnt(0)
	s_barrier
	s_waitcnt lgkmcnt(0)
	v_mfma_f32_16x16x32_bf16 v[76:79], v[56:59], v[188:191], v[76:79]
	v_mfma_f32_16x16x32_bf16 v[72:75], v[64:67], v[188:191], v[72:75]
	v_mfma_f32_16x16x32_bf16 v[44:47], v[56:59], v[196:199], v[44:47]
	v_mfma_f32_16x16x32_bf16 v[40:43], v[64:67], v[196:199], v[40:43]
	v_mfma_f32_16x16x32_bf16 v[28:31], v[56:59], v[204:207], v[28:31]
	v_mfma_f32_16x16x32_bf16 v[24:27], v[64:67], v[204:207], v[24:27]
	v_mfma_f32_16x16x32_bf16 v[12:15], v[56:59], v[212:215], v[12:15]
	v_mfma_f32_16x16x32_bf16 v[8:11], v[64:67], v[212:215], v[8:11]
	v_mfma_f32_16x16x32_bf16 v[76:79], v[60:63], v[192:195], v[76:79]
	v_mfma_f32_16x16x32_bf16 v[72:75], v[68:71], v[192:195], v[72:75]
	v_mfma_f32_16x16x32_bf16 v[44:47], v[60:63], v[200:203], v[44:47]
	v_mfma_f32_16x16x32_bf16 v[40:43], v[68:71], v[200:203], v[40:43]
	v_mfma_f32_16x16x32_bf16 v[28:31], v[60:63], v[208:211], v[28:31]
	v_mfma_f32_16x16x32_bf16 v[24:27], v[68:71], v[208:211], v[24:27]
	v_mfma_f32_16x16x32_bf16 v[12:15], v[60:63], v[216:219], v[12:15]
	v_mfma_f32_16x16x32_bf16 v[8:11], v[68:71], v[216:219], v[8:11]
	v_mfma_f32_16x16x32_bf16 v[52:55], v[164:167], v[188:191], v[52:55]
	v_mfma_f32_16x16x32_bf16 v[48:51], v[180:183], v[188:191], v[48:51]
	v_mfma_f32_16x16x32_bf16 v[36:39], v[164:167], v[196:199], v[36:39]
	v_mfma_f32_16x16x32_bf16 v[32:35], v[180:183], v[196:199], v[32:35]
	v_mfma_f32_16x16x32_bf16 v[20:23], v[164:167], v[204:207], v[20:23]
	v_mfma_f32_16x16x32_bf16 v[16:19], v[180:183], v[204:207], v[16:19]
	v_mfma_f32_16x16x32_bf16 v[4:7], v[164:167], v[212:215], v[4:7]
	v_mfma_f32_16x16x32_bf16 v[0:3], v[180:183], v[212:215], v[0:3]
	v_mfma_f32_16x16x32_bf16 v[52:55], v[168:171], v[192:195], v[52:55]
	v_mfma_f32_16x16x32_bf16 v[48:51], v[184:187], v[192:195], v[48:51]
	v_mfma_f32_16x16x32_bf16 v[36:39], v[168:171], v[200:203], v[36:39]
	v_mfma_f32_16x16x32_bf16 v[32:35], v[184:187], v[200:203], v[32:35]
	v_mfma_f32_16x16x32_bf16 v[20:23], v[168:171], v[208:211], v[20:23]
	v_mfma_f32_16x16x32_bf16 v[16:19], v[184:187], v[208:211], v[16:19]
	v_mfma_f32_16x16x32_bf16 v[4:7], v[168:171], v[216:219], v[4:7]
	v_mfma_f32_16x16x32_bf16 v[0:3], v[184:187], v[216:219], v[0:3]
	s_barrier
	s_add_i32 s54, 0, 0x18000
	s_add_i32 s55, 0, 0x1c000
	v_add_u32_e32 v68, s54, v174
	v_add_u32_e32 v152, s55, v174
	ds_read_b128 v[56:59], v68
	ds_read_b128 v[60:63], v68 offset:1024
	ds_read_b128 v[64:67], v68 offset:2048
	ds_read_b128 v[68:71], v68 offset:3072
	ds_read_b128 v[164:167], v152
	ds_read_b128 v[168:171], v152 offset:1024
	ds_read_b128 v[180:183], v152 offset:2048
	ds_read_b128 v[184:187], v152 offset:3072
	s_add_u32 s26, s60, 0x1000
	s_addc_u32 s27, s61, 0
	s_mov_b32 m0, s64
	v_lshl_add_u64 v[222:223], s[26:27], 0, v[144:145]
	ds_read_b128 v[188:191], v178 offset:32768
	ds_read_b128 v[192:195], v178 offset:33792
	ds_read_b128 v[196:199], v178 offset:34816
	ds_read_b128 v[200:203], v178 offset:35840
	ds_read_b128 v[204:207], v178 offset:36864
	ds_read_b128 v[208:211], v178 offset:37888
	ds_read_b128 v[212:215], v178 offset:38912
	ds_read_b128 v[216:219], v178 offset:39936
	global_load_lds_dwordx4 v[222:223], off
	v_lshl_add_u64 v[222:223], s[26:27], 0, v[148:149]
	s_mov_b32 m0, s65
	s_nop 0
	global_load_lds_dwordx4 v[222:223], off
	s_waitcnt vmcnt(8)
	s_waitcnt lgkmcnt(0)
	s_barrier
	s_waitcnt lgkmcnt(0)
	v_mfma_f32_16x16x32_bf16 v[140:143], v[56:59], v[188:191], v[140:143]
	v_mfma_f32_16x16x32_bf16 v[136:139], v[64:67], v[188:191], v[136:139]
	v_mfma_f32_16x16x32_bf16 v[124:127], v[56:59], v[196:199], v[124:127]
	v_mfma_f32_16x16x32_bf16 v[120:123], v[64:67], v[196:199], v[120:123]
	v_mfma_f32_16x16x32_bf16 v[108:111], v[56:59], v[204:207], v[108:111]
	v_mfma_f32_16x16x32_bf16 v[104:107], v[64:67], v[204:207], v[104:107]
	v_mfma_f32_16x16x32_bf16 v[92:95], v[56:59], v[212:215], v[92:95]
	v_mfma_f32_16x16x32_bf16 v[88:91], v[64:67], v[212:215], v[88:91]
	v_mfma_f32_16x16x32_bf16 v[140:143], v[60:63], v[192:195], v[140:143]
	v_mfma_f32_16x16x32_bf16 v[136:139], v[68:71], v[192:195], v[136:139]
	v_mfma_f32_16x16x32_bf16 v[124:127], v[60:63], v[200:203], v[124:127]
	v_mfma_f32_16x16x32_bf16 v[120:123], v[68:71], v[200:203], v[120:123]
	v_mfma_f32_16x16x32_bf16 v[108:111], v[60:63], v[208:211], v[108:111]
	v_mfma_f32_16x16x32_bf16 v[104:107], v[68:71], v[208:211], v[104:107]
	v_mfma_f32_16x16x32_bf16 v[92:95], v[60:63], v[216:219], v[92:95]
	v_mfma_f32_16x16x32_bf16 v[88:91], v[68:71], v[216:219], v[88:91]
	v_mfma_f32_16x16x32_bf16 v[132:135], v[164:167], v[188:191], v[132:135]
	v_mfma_f32_16x16x32_bf16 v[128:131], v[180:183], v[188:191], v[128:131]
	v_mfma_f32_16x16x32_bf16 v[116:119], v[164:167], v[196:199], v[116:119]
	v_mfma_f32_16x16x32_bf16 v[112:115], v[180:183], v[196:199], v[112:115]
	v_mfma_f32_16x16x32_bf16 v[100:103], v[164:167], v[204:207], v[100:103]
	v_mfma_f32_16x16x32_bf16 v[96:99], v[180:183], v[204:207], v[96:99]
	v_mfma_f32_16x16x32_bf16 v[84:87], v[164:167], v[212:215], v[84:87]
	v_mfma_f32_16x16x32_bf16 v[80:83], v[180:183], v[212:215], v[80:83]
	v_mfma_f32_16x16x32_bf16 v[132:135], v[168:171], v[192:195], v[132:135]
	v_mfma_f32_16x16x32_bf16 v[128:131], v[184:187], v[192:195], v[128:131]
	v_mfma_f32_16x16x32_bf16 v[116:119], v[168:171], v[200:203], v[116:119]
	v_mfma_f32_16x16x32_bf16 v[112:115], v[184:187], v[200:203], v[112:115]
	v_mfma_f32_16x16x32_bf16 v[100:103], v[168:171], v[208:211], v[100:103]
	v_mfma_f32_16x16x32_bf16 v[96:99], v[184:187], v[208:211], v[96:99]
	v_mfma_f32_16x16x32_bf16 v[84:87], v[168:171], v[216:219], v[84:87]
	v_mfma_f32_16x16x32_bf16 v[80:83], v[184:187], v[216:219], v[80:83]
	s_barrier
	s_add_i32 s26, s54, s3
	v_lshl_add_u64 v[172:173], v[172:173], 0, s[24:25]
	s_mov_b32 m0, s26
	ds_read_b128 v[188:191], v178 offset:49152
	ds_read_b128 v[192:195], v178 offset:50176
	ds_read_b128 v[196:199], v178 offset:51200
	ds_read_b128 v[200:203], v178 offset:52224
	ds_read_b128 v[204:207], v178 offset:53248
	ds_read_b128 v[208:211], v178 offset:54272
	ds_read_b128 v[212:215], v178 offset:55296
	ds_read_b128 v[216:219], v178 offset:56320
	global_load_lds_dwordx4 v[172:173], off
	s_add_i32 m0, s26, 0x2000
	s_add_u32 s26, s58, 0x20080
	v_lshl_add_u64 v[172:173], v[220:221], 0, s[24:25]
	s_addc_u32 s27, s59, 0
	s_add_i32 s54, s55, s3
	global_load_lds_dwordx4 v[172:173], off
	v_lshl_add_u64 v[172:173], s[26:27], 0, v[146:147]
	s_mov_b32 m0, s54
	s_nop 0
	global_load_lds_dwordx4 v[172:173], off
	v_lshl_add_u64 v[172:173], s[26:27], 0, v[150:151]
	s_add_i32 m0, s54, 0x2000
	s_nop 0
	global_load_lds_dwordx4 v[172:173], off
	v_lshl_add_u64 v[172:173], s[56:57], 0, v[144:145]
	s_mov_b32 m0, s67
	s_nop 0
	global_load_lds_dwordx4 v[172:173], off
	v_lshl_add_u64 v[172:173], s[56:57], 0, v[148:149]
	s_mov_b32 m0, s68
	s_nop 0
	global_load_lds_dwordx4 v[172:173], off
	s_waitcnt vmcnt(8)
	s_waitcnt lgkmcnt(0)
	s_barrier
	s_waitcnt lgkmcnt(0)
	v_mfma_f32_16x16x32_bf16 v[76:79], v[56:59], v[188:191], v[76:79]
	v_mfma_f32_16x16x32_bf16 v[72:75], v[64:67], v[188:191], v[72:75]
	v_mfma_f32_16x16x32_bf16 v[44:47], v[56:59], v[196:199], v[44:47]
	v_mfma_f32_16x16x32_bf16 v[40:43], v[64:67], v[196:199], v[40:43]
	v_mfma_f32_16x16x32_bf16 v[28:31], v[56:59], v[204:207], v[28:31]
	v_mfma_f32_16x16x32_bf16 v[24:27], v[64:67], v[204:207], v[24:27]
	v_mfma_f32_16x16x32_bf16 v[12:15], v[56:59], v[212:215], v[12:15]
	v_mfma_f32_16x16x32_bf16 v[8:11], v[64:67], v[212:215], v[8:11]
	v_mfma_f32_16x16x32_bf16 v[76:79], v[60:63], v[192:195], v[76:79]
	v_mfma_f32_16x16x32_bf16 v[72:75], v[68:71], v[192:195], v[72:75]
	v_mfma_f32_16x16x32_bf16 v[44:47], v[60:63], v[200:203], v[44:47]
	v_mfma_f32_16x16x32_bf16 v[40:43], v[68:71], v[200:203], v[40:43]
	v_mfma_f32_16x16x32_bf16 v[28:31], v[60:63], v[208:211], v[28:31]
	v_mfma_f32_16x16x32_bf16 v[24:27], v[68:71], v[208:211], v[24:27]
	v_mfma_f32_16x16x32_bf16 v[12:15], v[60:63], v[216:219], v[12:15]
	v_mfma_f32_16x16x32_bf16 v[8:11], v[68:71], v[216:219], v[8:11]
	v_mfma_f32_16x16x32_bf16 v[52:55], v[164:167], v[188:191], v[52:55]
	v_mfma_f32_16x16x32_bf16 v[48:51], v[180:183], v[188:191], v[48:51]
	v_mfma_f32_16x16x32_bf16 v[36:39], v[164:167], v[196:199], v[36:39]
	v_mfma_f32_16x16x32_bf16 v[32:35], v[180:183], v[196:199], v[32:35]
	v_mfma_f32_16x16x32_bf16 v[20:23], v[164:167], v[204:207], v[20:23]
	v_mfma_f32_16x16x32_bf16 v[16:19], v[180:183], v[204:207], v[16:19]
	v_mfma_f32_16x16x32_bf16 v[4:7], v[164:167], v[212:215], v[4:7]
	v_mfma_f32_16x16x32_bf16 v[0:3], v[180:183], v[212:215], v[0:3]
	v_mfma_f32_16x16x32_bf16 v[52:55], v[168:171], v[192:195], v[52:55]
	v_mfma_f32_16x16x32_bf16 v[48:51], v[184:187], v[192:195], v[48:51]
	v_mfma_f32_16x16x32_bf16 v[36:39], v[168:171], v[200:203], v[36:39]
	v_mfma_f32_16x16x32_bf16 v[32:35], v[184:187], v[200:203], v[32:35]
	v_mfma_f32_16x16x32_bf16 v[20:23], v[168:171], v[208:211], v[20:23]
	v_mfma_f32_16x16x32_bf16 v[16:19], v[184:187], v[208:211], v[16:19]
	v_mfma_f32_16x16x32_bf16 v[4:7], v[168:171], v[216:219], v[4:7]
	v_mfma_f32_16x16x32_bf16 v[0:3], v[184:187], v[216:219], v[0:3]
	s_barrier
	s_add_i32 s80, s80, 2
	s_add_u32 s76, s76, 0x100
	s_addc_u32 s77, s77, 0
	s_add_u32 s52, s52, 0x800000
	s_addc_u32 s53, s53, 0
	s_cmp_gt_u32 s80, 5
	s_cbranch_scc0 .LBB0_635
	s_and_b64 vcc, exec, s[36:37]
	s_cbranch_vccz .LBB0_638
	s_barrier

.LBB0_739:
	v_add_u32_e32 v1, s74, v163
	ds_read_b128 v[156:159], v1
	ds_read_b128 v[168:171], v1 offset:1024
	ds_read_b128 v[172:175], v1 offset:2048
	ds_read_b128 v[176:179], v1 offset:3072
	v_add_u32_e32 v1, s75, v163
	s_add_u32 s26, s58, s60
	ds_read_b128 v[180:183], v1
	ds_read_b128 v[184:187], v1 offset:1024
	ds_read_b128 v[188:191], v1 offset:2048
	ds_read_b128 v[192:195], v1 offset:3072
	s_addc_u32 s27, s59, s61
	s_add_u32 s26, s26, 0x100
	s_addc_u32 s27, s27, 0
	s_add_u32 s54, s79, s60
	s_addc_u32 s55, s80, s61
	s_cmpk_eq_i32 s60, 0x700
	s_cselect_b32 s65, s51, s27
	s_cselect_b32 s64, s77, s26
	s_cselect_b32 s63, s45, s55
	s_cselect_b32 s62, s78, s54
	v_lshl_add_u64 v[2:3], v[152:153], 0, s[60:61]
	s_add_i32 m0, s67, 0xc000
	ds_read_b128 v[196:199], v165
	ds_read_b128 v[200:203], v165 offset:1024
	ds_read_b128 v[204:207], v165 offset:2048
	ds_read_b128 v[208:211], v165 offset:3072
	ds_read_b128 v[212:215], v165 offset:4096
	ds_read_b128 v[216:219], v165 offset:5120
	ds_read_b128 v[220:223], v165 offset:6144
	ds_read_b128 v[224:227], v165 offset:7168
	global_load_lds_dwordx4 v[2:3], off
	v_lshl_add_u64 v[2:3], v[154:155], 0, s[60:61]
	s_add_i32 m0, s67, 0xe000
	s_nop 0
	global_load_lds_dwordx4 v[2:3], off
	s_waitcnt vmcnt(8)
	s_waitcnt lgkmcnt(0)
	s_barrier
	s_waitcnt lgkmcnt(0)
	v_mfma_f32_16x16x32_bf16 v[128:131], v[156:159], v[196:199], v[128:131]
	v_mfma_f32_16x16x32_bf16 v[124:127], v[172:175], v[196:199], v[124:127]
	v_mfma_f32_16x16x32_bf16 v[112:115], v[156:159], v[204:207], v[112:115]
	v_mfma_f32_16x16x32_bf16 v[108:111], v[172:175], v[204:207], v[108:111]
	v_mfma_f32_16x16x32_bf16 v[96:99], v[156:159], v[212:215], v[96:99]
	v_mfma_f32_16x16x32_bf16 v[92:95], v[172:175], v[212:215], v[92:95]
	v_mfma_f32_16x16x32_bf16 v[80:83], v[156:159], v[220:223], v[80:83]
	v_mfma_f32_16x16x32_bf16 v[76:79], v[172:175], v[220:223], v[76:79]
	v_mfma_f32_16x16x32_bf16 v[128:131], v[168:171], v[200:203], v[128:131]
	v_mfma_f32_16x16x32_bf16 v[124:127], v[176:179], v[200:203], v[124:127]
	v_mfma_f32_16x16x32_bf16 v[112:115], v[168:171], v[208:211], v[112:115]
	v_mfma_f32_16x16x32_bf16 v[108:111], v[176:179], v[208:211], v[108:111]
	v_mfma_f32_16x16x32_bf16 v[96:99], v[168:171], v[216:219], v[96:99]
	v_mfma_f32_16x16x32_bf16 v[92:95], v[176:179], v[216:219], v[92:95]
	v_mfma_f32_16x16x32_bf16 v[80:83], v[168:171], v[224:227], v[80:83]
	v_mfma_f32_16x16x32_bf16 v[76:79], v[176:179], v[224:227], v[76:79]
	v_mfma_f32_16x16x32_bf16 v[120:123], v[180:183], v[196:199], v[120:123]
	v_mfma_f32_16x16x32_bf16 v[116:119], v[188:191], v[196:199], v[116:119]
	v_mfma_f32_16x16x32_bf16 v[104:107], v[180:183], v[204:207], v[104:107]
	v_mfma_f32_16x16x32_bf16 v[100:103], v[188:191], v[204:207], v[100:103]
	v_mfma_f32_16x16x32_bf16 v[88:91], v[180:183], v[212:215], v[88:91]
	v_mfma_f32_16x16x32_bf16 v[84:87], v[188:191], v[212:215], v[84:87]
	v_mfma_f32_16x16x32_bf16 v[72:75], v[180:183], v[220:223], v[72:75]
	v_mfma_f32_16x16x32_bf16 v[68:71], v[188:191], v[220:223], v[68:71]
	v_mfma_f32_16x16x32_bf16 v[120:123], v[184:187], v[200:203], v[120:123]
	v_mfma_f32_16x16x32_bf16 v[116:119], v[192:195], v[200:203], v[116:119]
	v_mfma_f32_16x16x32_bf16 v[104:107], v[184:187], v[208:211], v[104:107]
	v_mfma_f32_16x16x32_bf16 v[100:103], v[192:195], v[208:211], v[100:103]
	v_mfma_f32_16x16x32_bf16 v[88:91], v[184:187], v[216:219], v[88:91]
	v_mfma_f32_16x16x32_bf16 v[84:87], v[192:195], v[216:219], v[84:87]
	v_mfma_f32_16x16x32_bf16 v[72:75], v[184:187], v[224:227], v[72:75]
	v_mfma_f32_16x16x32_bf16 v[68:71], v[192:195], v[224:227], v[68:71]
	s_barrier
	s_add_i32 s26, s74, s66
	v_lshl_add_u64 v[160:161], s[62:63], 0, v[134:135]
	s_mov_b32 m0, s26
	ds_read_b128 v[196:199], v165 offset:16384
	ds_read_b128 v[200:203], v165 offset:17408
	ds_read_b128 v[204:207], v165 offset:18432
	ds_read_b128 v[208:211], v165 offset:19456
	ds_read_b128 v[212:215], v165 offset:20480
	ds_read_b128 v[216:219], v165 offset:21504
	ds_read_b128 v[220:223], v165 offset:22528
	ds_read_b128 v[224:227], v165 offset:23552
	global_load_lds_dwordx4 v[160:161], off
	s_add_i32 m0, s26, 0x2000
	s_add_u32 s26, s62, 0x40000
	v_lshl_add_u64 v[228:229], s[62:63], 0, v[138:139]
	s_addc_u32 s27, s63, 0
	s_add_i32 s54, s75, s66
	global_load_lds_dwordx4 v[228:229], off
	v_lshl_add_u64 v[2:3], s[26:27], 0, v[134:135]
	s_mov_b32 m0, s54
	v_lshl_add_u64 v[230:231], s[64:65], 0, v[132:133]
	global_load_lds_dwordx4 v[2:3], off
	v_lshl_add_u64 v[2:3], s[26:27], 0, v[138:139]
	s_add_i32 m0, s54, 0x2000
	v_lshl_add_u64 v[232:233], s[64:65], 0, v[136:137]
	global_load_lds_dwordx4 v[2:3], off
	s_mov_b32 m0, s67
	s_nop 0
	global_load_lds_dwordx4 v[230:231], off
	s_mov_b32 m0, s68
	s_nop 0
	global_load_lds_dwordx4 v[232:233], off
	s_waitcnt vmcnt(8)
	s_waitcnt lgkmcnt(0)
	s_barrier
	s_waitcnt lgkmcnt(0)
	v_mfma_f32_16x16x32_bf16 v[64:67], v[156:159], v[196:199], v[64:67]
	v_mfma_f32_16x16x32_bf16 v[60:63], v[172:175], v[196:199], v[60:63]
	v_mfma_f32_16x16x32_bf16 v[48:51], v[156:159], v[204:207], v[48:51]
	v_mfma_f32_16x16x32_bf16 v[44:47], v[172:175], v[204:207], v[44:47]
	v_mfma_f32_16x16x32_bf16 v[32:35], v[156:159], v[212:215], v[32:35]
	v_mfma_f32_16x16x32_bf16 v[28:31], v[172:175], v[212:215], v[28:31]
	v_mfma_f32_16x16x32_bf16 v[16:19], v[156:159], v[220:223], v[16:19]
	v_mfma_f32_16x16x32_bf16 v[12:15], v[172:175], v[220:223], v[12:15]
	v_mfma_f32_16x16x32_bf16 v[64:67], v[168:171], v[200:203], v[64:67]
	v_mfma_f32_16x16x32_bf16 v[60:63], v[176:179], v[200:203], v[60:63]
	v_mfma_f32_16x16x32_bf16 v[48:51], v[168:171], v[208:211], v[48:51]
	v_mfma_f32_16x16x32_bf16 v[44:47], v[176:179], v[208:211], v[44:47]
	v_mfma_f32_16x16x32_bf16 v[32:35], v[168:171], v[216:219], v[32:35]
	v_mfma_f32_16x16x32_bf16 v[28:31], v[176:179], v[216:219], v[28:31]
	v_mfma_f32_16x16x32_bf16 v[16:19], v[168:171], v[224:227], v[16:19]
	v_mfma_f32_16x16x32_bf16 v[12:15], v[176:179], v[224:227], v[12:15]
	v_mfma_f32_16x16x32_bf16 v[56:59], v[180:183], v[196:199], v[56:59]
	v_mfma_f32_16x16x32_bf16 v[52:55], v[188:191], v[196:199], v[52:55]
	v_mfma_f32_16x16x32_bf16 v[40:43], v[180:183], v[204:207], v[40:43]
	v_mfma_f32_16x16x32_bf16 v[36:39], v[188:191], v[204:207], v[36:39]
	v_mfma_f32_16x16x32_bf16 v[24:27], v[180:183], v[212:215], v[24:27]
	v_mfma_f32_16x16x32_bf16 v[20:23], v[188:191], v[212:215], v[20:23]
	v_mfma_f32_16x16x32_bf16 v[8:11], v[180:183], v[220:223], v[8:11]
	v_mfma_f32_16x16x32_bf16 v[2:5], v[188:191], v[220:223], v[4:7]
	v_mfma_f32_16x16x32_bf16 v[56:59], v[184:187], v[200:203], v[56:59]
	v_mfma_f32_16x16x32_bf16 v[52:55], v[192:195], v[200:203], v[52:55]
	v_mfma_f32_16x16x32_bf16 v[40:43], v[184:187], v[208:211], v[40:43]
	v_mfma_f32_16x16x32_bf16 v[36:39], v[192:195], v[208:211], v[36:39]
	v_mfma_f32_16x16x32_bf16 v[24:27], v[184:187], v[216:219], v[24:27]
	v_mfma_f32_16x16x32_bf16 v[20:23], v[192:195], v[216:219], v[20:23]
	v_mfma_f32_16x16x32_bf16 v[8:11], v[184:187], v[224:227], v[8:11]
	v_mfma_f32_16x16x32_bf16 v[2:5], v[192:195], v[224:227], v[2:5]
	s_barrier
	s_add_i32 s54, 0, 0x18000
	v_add_u32_e32 v1, s54, v163
	s_add_i32 s55, 0, 0x1c000
	ds_read_b128 v[156:159], v1
	ds_read_b128 v[168:171], v1 offset:1024
	ds_read_b128 v[172:175], v1 offset:2048
	ds_read_b128 v[176:179], v1 offset:3072
	v_add_u32_e32 v1, s55, v163
	ds_read_b128 v[180:183], v1
	ds_read_b128 v[184:187], v1 offset:1024
	ds_read_b128 v[188:191], v1 offset:2048
	ds_read_b128 v[192:195], v1 offset:3072
	s_add_u32 s26, s64, 0x40000
	s_addc_u32 s27, s65, 0
	s_mov_b32 m0, s69
	v_lshl_add_u64 v[6:7], s[26:27], 0, v[132:133]
	ds_read_b128 v[196:199], v165 offset:32768
	ds_read_b128 v[200:203], v165 offset:33792
	ds_read_b128 v[204:207], v165 offset:34816
	ds_read_b128 v[208:211], v165 offset:35840
	ds_read_b128 v[212:215], v165 offset:36864
	ds_read_b128 v[216:219], v165 offset:37888
	ds_read_b128 v[220:223], v165 offset:38912
	ds_read_b128 v[224:227], v165 offset:39936
	global_load_lds_dwordx4 v[6:7], off
	v_lshl_add_u64 v[6:7], s[26:27], 0, v[136:137]
	s_mov_b32 m0, s70
	s_nop 0
	global_load_lds_dwordx4 v[6:7], off
	s_waitcnt vmcnt(8)
	s_waitcnt lgkmcnt(0)
	s_barrier
	s_waitcnt lgkmcnt(0)
	v_mfma_f32_16x16x32_bf16 v[128:131], v[156:159], v[196:199], v[128:131]
	v_mfma_f32_16x16x32_bf16 v[124:127], v[172:175], v[196:199], v[124:127]
	v_mfma_f32_16x16x32_bf16 v[112:115], v[156:159], v[204:207], v[112:115]
	v_mfma_f32_16x16x32_bf16 v[108:111], v[172:175], v[204:207], v[108:111]
	v_mfma_f32_16x16x32_bf16 v[96:99], v[156:159], v[212:215], v[96:99]
	v_mfma_f32_16x16x32_bf16 v[92:95], v[172:175], v[212:215], v[92:95]
	v_mfma_f32_16x16x32_bf16 v[80:83], v[156:159], v[220:223], v[80:83]
	v_mfma_f32_16x16x32_bf16 v[76:79], v[172:175], v[220:223], v[76:79]
	v_mfma_f32_16x16x32_bf16 v[128:131], v[168:171], v[200:203], v[128:131]
	v_mfma_f32_16x16x32_bf16 v[124:127], v[176:179], v[200:203], v[124:127]
	v_mfma_f32_16x16x32_bf16 v[112:115], v[168:171], v[208:211], v[112:115]
	v_mfma_f32_16x16x32_bf16 v[108:111], v[176:179], v[208:211], v[108:111]
	v_mfma_f32_16x16x32_bf16 v[96:99], v[168:171], v[216:219], v[96:99]
	v_mfma_f32_16x16x32_bf16 v[92:95], v[176:179], v[216:219], v[92:95]
	v_mfma_f32_16x16x32_bf16 v[80:83], v[168:171], v[224:227], v[80:83]
	v_mfma_f32_16x16x32_bf16 v[76:79], v[176:179], v[224:227], v[76:79]
	v_mfma_f32_16x16x32_bf16 v[120:123], v[180:183], v[196:199], v[120:123]
	v_mfma_f32_16x16x32_bf16 v[116:119], v[188:191], v[196:199], v[116:119]
	v_mfma_f32_16x16x32_bf16 v[104:107], v[180:183], v[204:207], v[104:107]
	v_mfma_f32_16x16x32_bf16 v[100:103], v[188:191], v[204:207], v[100:103]
	v_mfma_f32_16x16x32_bf16 v[88:91], v[180:183], v[212:215], v[88:91]
	v_mfma_f32_16x16x32_bf16 v[84:87], v[188:191], v[212:215], v[84:87]
	v_mfma_f32_16x16x32_bf16 v[72:75], v[180:183], v[220:223], v[72:75]
	v_mfma_f32_16x16x32_bf16 v[68:71], v[188:191], v[220:223], v[68:71]
	v_mfma_f32_16x16x32_bf16 v[120:123], v[184:187], v[200:203], v[120:123]
	v_mfma_f32_16x16x32_bf16 v[116:119], v[192:195], v[200:203], v[116:119]
	v_mfma_f32_16x16x32_bf16 v[104:107], v[184:187], v[208:211], v[104:107]
	v_mfma_f32_16x16x32_bf16 v[100:103], v[192:195], v[208:211], v[100:103]
	v_mfma_f32_16x16x32_bf16 v[88:91], v[184:187], v[216:219], v[88:91]
	v_mfma_f32_16x16x32_bf16 v[84:87], v[192:195], v[216:219], v[84:87]
	v_mfma_f32_16x16x32_bf16 v[72:75], v[184:187], v[224:227], v[72:75]
	v_mfma_f32_16x16x32_bf16 v[68:71], v[192:195], v[224:227], v[68:71]
	s_barrier
	s_add_i32 s26, s54, s66
	v_lshl_add_u64 v[6:7], v[160:161], 0, s[40:41]
	s_mov_b32 m0, s26
	ds_read_b128 v[196:199], v165 offset:49152
	ds_read_b128 v[200:203], v165 offset:50176
	ds_read_b128 v[204:207], v165 offset:51200
	ds_read_b128 v[208:211], v165 offset:52224
	ds_read_b128 v[212:215], v165 offset:53248
	ds_read_b128 v[216:219], v165 offset:54272
	ds_read_b128 v[220:223], v165 offset:55296
	ds_read_b128 v[224:227], v165 offset:56320
	global_load_lds_dwordx4 v[6:7], off
	s_add_i32 m0, s26, 0x2000
	s_add_u32 s26, s62, 0x40080
	v_lshl_add_u64 v[6:7], v[228:229], 0, s[40:41]
	s_addc_u32 s27, s63, 0
	s_add_i32 s54, s55, s66
	global_load_lds_dwordx4 v[6:7], off
	v_lshl_add_u64 v[6:7], s[26:27], 0, v[134:135]
	s_mov_b32 m0, s54
	s_nop 0
	global_load_lds_dwordx4 v[6:7], off
	v_lshl_add_u64 v[6:7], s[26:27], 0, v[138:139]
	s_add_i32 m0, s54, 0x2000
	s_nop 0
	global_load_lds_dwordx4 v[6:7], off
	v_lshl_add_u64 v[6:7], v[230:231], 0, s[40:41]
	s_mov_b32 m0, s72
	s_nop 0
	global_load_lds_dwordx4 v[6:7], off
	v_lshl_add_u64 v[6:7], v[232:233], 0, s[40:41]
	s_mov_b32 m0, s73
	s_nop 0
	global_load_lds_dwordx4 v[6:7], off
	s_waitcnt vmcnt(8)
	s_waitcnt lgkmcnt(0)
	s_barrier
	s_waitcnt lgkmcnt(0)
	v_mfma_f32_16x16x32_bf16 v[64:67], v[156:159], v[196:199], v[64:67]
	v_mfma_f32_16x16x32_bf16 v[60:63], v[172:175], v[196:199], v[60:63]
	v_mfma_f32_16x16x32_bf16 v[48:51], v[156:159], v[204:207], v[48:51]
	v_mfma_f32_16x16x32_bf16 v[44:47], v[172:175], v[204:207], v[44:47]
	v_mfma_f32_16x16x32_bf16 v[32:35], v[156:159], v[212:215], v[32:35]
	v_mfma_f32_16x16x32_bf16 v[28:31], v[172:175], v[212:215], v[28:31]
	v_mfma_f32_16x16x32_bf16 v[16:19], v[156:159], v[220:223], v[16:19]
	v_mfma_f32_16x16x32_bf16 v[12:15], v[172:175], v[220:223], v[12:15]
	v_mfma_f32_16x16x32_bf16 v[64:67], v[168:171], v[200:203], v[64:67]
	v_mfma_f32_16x16x32_bf16 v[60:63], v[176:179], v[200:203], v[60:63]
	v_mfma_f32_16x16x32_bf16 v[48:51], v[168:171], v[208:211], v[48:51]
	v_mfma_f32_16x16x32_bf16 v[44:47], v[176:179], v[208:211], v[44:47]
	v_mfma_f32_16x16x32_bf16 v[32:35], v[168:171], v[216:219], v[32:35]
	v_mfma_f32_16x16x32_bf16 v[28:31], v[176:179], v[216:219], v[28:31]
	v_mfma_f32_16x16x32_bf16 v[16:19], v[168:171], v[224:227], v[16:19]
	v_mfma_f32_16x16x32_bf16 v[12:15], v[176:179], v[224:227], v[12:15]
	v_mfma_f32_16x16x32_bf16 v[56:59], v[180:183], v[196:199], v[56:59]
	v_mfma_f32_16x16x32_bf16 v[52:55], v[188:191], v[196:199], v[52:55]
	v_mfma_f32_16x16x32_bf16 v[40:43], v[180:183], v[204:207], v[40:43]
	v_mfma_f32_16x16x32_bf16 v[36:39], v[188:191], v[204:207], v[36:39]
	v_mfma_f32_16x16x32_bf16 v[24:27], v[180:183], v[212:215], v[24:27]
	v_mfma_f32_16x16x32_bf16 v[20:23], v[188:191], v[212:215], v[20:23]
	v_mfma_f32_16x16x32_bf16 v[6:9], v[180:183], v[220:223], v[8:11]
	v_mfma_f32_16x16x32_bf16 v[2:5], v[188:191], v[220:223], v[2:5]
	v_mfma_f32_16x16x32_bf16 v[56:59], v[184:187], v[200:203], v[56:59]
	v_mfma_f32_16x16x32_bf16 v[52:55], v[192:195], v[200:203], v[52:55]
	v_mfma_f32_16x16x32_bf16 v[40:43], v[184:187], v[208:211], v[40:43]
	v_mfma_f32_16x16x32_bf16 v[36:39], v[192:195], v[208:211], v[36:39]
	v_mfma_f32_16x16x32_bf16 v[24:27], v[184:187], v[216:219], v[24:27]
	v_mfma_f32_16x16x32_bf16 v[20:23], v[192:195], v[216:219], v[20:23]
	v_mfma_f32_16x16x32_bf16 v[8:11], v[184:187], v[224:227], v[6:9]
	v_mfma_f32_16x16x32_bf16 v[4:7], v[192:195], v[224:227], v[2:5]
	s_barrier
	s_add_i32 s81, s81, 2
	s_add_u32 s60, s60, 0x100
	s_addc_u32 s61, s61, 0
	s_cmp_gt_u32 s81, 13
	s_cbranch_scc1 .LBB0_742

.LBB0_882:
	ds_read_b128 v[64:67], v238
	ds_read_b128 v[68:71], v238 offset:1024
	ds_read_b128 v[152:155], v238 offset:2048
	ds_read_b128 v[156:159], v238 offset:3072
	ds_read_b128 v[160:163], v239
	ds_read_b128 v[164:167], v239 offset:1024
	ds_read_b128 v[168:171], v239 offset:2048
	ds_read_b128 v[172:175], v239 offset:3072
	s_add_u32 s64, s62, 0x100
	s_addc_u32 s65, s63, 0
	s_cmp_eq_u32 s96, 12
	s_cselect_b32 s69, s53, s65
	s_cselect_b32 s68, s59, s64
	s_cselect_b32 s67, s51, s95
	s_cselect_b32 s66, s61, s94
	v_lshl_add_u64 v[208:209], s[62:63], 0, v[144:145]
	s_add_i32 m0, s71, 0xc000
	ds_read_b128 v[176:179], v240
	ds_read_b128 v[180:183], v240 offset:1024
	ds_read_b128 v[184:187], v240 offset:2048
	ds_read_b128 v[188:191], v240 offset:3072
	ds_read_b128 v[192:195], v240 offset:4096
	ds_read_b128 v[196:199], v240 offset:5120
	ds_read_b128 v[200:203], v240 offset:6144
	ds_read_b128 v[204:207], v240 offset:7168
	global_load_lds_dwordx4 v[208:209], off
	v_lshl_add_u64 v[208:209], s[62:63], 0, v[146:147]
	s_add_i32 m0, s71, 0xe000
	s_nop 0
	global_load_lds_dwordx4 v[208:209], off
	s_waitcnt vmcnt(8)
	s_waitcnt lgkmcnt(0)
	s_barrier
	s_waitcnt lgkmcnt(0)
	v_mfma_f32_16x16x32_bf16 v[104:107], v[64:67], v[176:179], v[104:107]
	v_mfma_f32_16x16x32_bf16 v[96:99], v[152:155], v[176:179], v[96:99]
	v_mfma_f32_16x16x32_bf16 v[92:95], v[64:67], v[184:187], v[92:95]
	v_mfma_f32_16x16x32_bf16 v[88:91], v[152:155], v[184:187], v[88:91]
	v_mfma_f32_16x16x32_bf16 v[60:63], v[64:67], v[192:195], v[60:63]
	v_mfma_f32_16x16x32_bf16 v[28:31], v[152:155], v[192:195], v[28:31]
	v_mfma_f32_16x16x32_bf16 v[56:59], v[64:67], v[200:203], v[56:59]
	v_mfma_f32_16x16x32_bf16 v[24:27], v[152:155], v[200:203], v[24:27]
	v_mfma_f32_16x16x32_bf16 v[104:107], v[68:71], v[180:183], v[104:107]
	v_mfma_f32_16x16x32_bf16 v[96:99], v[156:159], v[180:183], v[96:99]
	v_mfma_f32_16x16x32_bf16 v[92:95], v[68:71], v[188:191], v[92:95]
	v_mfma_f32_16x16x32_bf16 v[88:91], v[156:159], v[188:191], v[88:91]
	v_mfma_f32_16x16x32_bf16 v[60:63], v[68:71], v[196:199], v[60:63]
	v_mfma_f32_16x16x32_bf16 v[28:31], v[156:159], v[196:199], v[28:31]
	v_mfma_f32_16x16x32_bf16 v[56:59], v[68:71], v[204:207], v[56:59]
	v_mfma_f32_16x16x32_bf16 v[24:27], v[156:159], v[204:207], v[24:27]
	v_mfma_f32_16x16x32_bf16 v[84:87], v[160:163], v[176:179], v[84:87]
	v_mfma_f32_16x16x32_bf16 v[80:83], v[168:171], v[176:179], v[80:83]
	v_mfma_f32_16x16x32_bf16 v[76:79], v[160:163], v[184:187], v[76:79]
	v_mfma_f32_16x16x32_bf16 v[72:75], v[168:171], v[184:187], v[72:75]
	v_mfma_f32_16x16x32_bf16 v[48:51], v[160:163], v[192:195], v[48:51]
	v_mfma_f32_16x16x32_bf16 v[16:19], v[168:171], v[192:195], v[16:19]
	v_mfma_f32_16x16x32_bf16 v[40:43], v[160:163], v[200:203], v[40:43]
	v_mfma_f32_16x16x32_bf16 v[8:11], v[168:171], v[200:203], v[8:11]
	v_mfma_f32_16x16x32_bf16 v[84:87], v[164:167], v[180:183], v[84:87]
	v_mfma_f32_16x16x32_bf16 v[80:83], v[172:175], v[180:183], v[80:83]
	v_mfma_f32_16x16x32_bf16 v[76:79], v[164:167], v[188:191], v[76:79]
	v_mfma_f32_16x16x32_bf16 v[72:75], v[172:175], v[188:191], v[72:75]
	v_mfma_f32_16x16x32_bf16 v[48:51], v[164:167], v[196:199], v[48:51]
	v_mfma_f32_16x16x32_bf16 v[16:19], v[172:175], v[196:199], v[16:19]
	v_mfma_f32_16x16x32_bf16 v[40:43], v[164:167], v[204:207], v[40:43]
	v_mfma_f32_16x16x32_bf16 v[8:11], v[172:175], v[204:207], v[8:11]
	s_barrier
	s_add_i32 s26, s88, s70
	v_lshl_add_u64 v[208:209], s[66:67], 0, v[138:139]
	s_mov_b32 m0, s26
	ds_read_b128 v[176:179], v240 offset:16384
	ds_read_b128 v[180:183], v240 offset:17408
	ds_read_b128 v[184:187], v240 offset:18432
	ds_read_b128 v[188:191], v240 offset:19456
	ds_read_b128 v[192:195], v240 offset:20480
	ds_read_b128 v[196:199], v240 offset:21504
	ds_read_b128 v[200:203], v240 offset:22528
	ds_read_b128 v[204:207], v240 offset:23552
	global_load_lds_dwordx4 v[208:209], off
	s_add_i32 m0, s26, 0x2000
	s_add_u32 s26, s66, 0x40000
	v_lshl_add_u64 v[210:211], s[66:67], 0, v[142:143]
	s_addc_u32 s27, s67, 0
	s_add_i32 s62, s89, s70
	global_load_lds_dwordx4 v[210:211], off
	v_lshl_add_u64 v[212:213], s[26:27], 0, v[138:139]
	s_mov_b32 m0, s62
	v_lshl_add_u64 v[214:215], s[68:69], 0, v[140:141]
	global_load_lds_dwordx4 v[212:213], off
	v_lshl_add_u64 v[212:213], s[26:27], 0, v[142:143]
	s_add_i32 m0, s62, 0x2000
	s_nop 0
	global_load_lds_dwordx4 v[212:213], off
	v_lshl_add_u64 v[212:213], s[68:69], 0, v[136:137]
	s_mov_b32 m0, s71
	s_nop 0
	global_load_lds_dwordx4 v[212:213], off
	s_mov_b32 m0, s72
	s_nop 0
	global_load_lds_dwordx4 v[214:215], off
	s_waitcnt vmcnt(8)
	v_mul_f32_e32 v248, s100, v226
	v_mul_f32_e32 v249, s100, v227
	ds_write_b64 v241, v[248:249]
	s_waitcnt lgkmcnt(0)
	s_barrier
	s_waitcnt lgkmcnt(0)
	v_mfma_f32_16x16x32_bf16 v[52:55], v[64:67], v[176:179], v[52:55]
	v_mfma_f32_16x16x32_bf16 v[20:23], v[152:155], v[176:179], v[20:23]
	v_mfma_f32_16x16x32_bf16 v[44:47], v[64:67], v[184:187], v[44:47]
	v_mfma_f32_16x16x32_bf16 v[12:15], v[152:155], v[184:187], v[12:15]
	v_mfma_f32_16x16x32_bf16 v[132:135], v[64:67], v[192:195], v[132:135]
	v_mfma_f32_16x16x32_bf16 v[128:131], v[152:155], v[192:195], v[128:131]
	v_mfma_f32_16x16x32_bf16 v[64:67], v[64:67], v[200:203], v[124:127]
	v_mfma_f32_16x16x32_bf16 v[52:55], v[68:71], v[180:183], v[52:55]
	v_mfma_f32_16x16x32_bf16 v[20:23], v[156:159], v[180:183], v[20:23]
	v_mfma_f32_16x16x32_bf16 v[44:47], v[68:71], v[188:191], v[44:47]
	v_mfma_f32_16x16x32_bf16 v[12:15], v[156:159], v[188:191], v[12:15]
	v_mfma_f32_16x16x32_bf16 v[132:135], v[68:71], v[196:199], v[132:135]
	v_mfma_f32_16x16x32_bf16 v[128:131], v[156:159], v[196:199], v[128:131]
	v_mfma_f32_16x16x32_bf16 v[64:67], v[68:71], v[204:207], v[64:67]
	v_mfma_f32_16x16x32_bf16 v[68:71], v[152:155], v[200:203], v[120:123]
	v_mfma_f32_16x16x32_bf16 v[68:71], v[156:159], v[204:207], v[68:71]
	v_mfma_f32_16x16x32_bf16 v[36:39], v[160:163], v[176:179], v[36:39]
	v_mfma_f32_16x16x32_bf16 v[4:7], v[168:171], v[176:179], v[4:7]
	v_mfma_f32_16x16x32_bf16 v[32:35], v[160:163], v[184:187], v[32:35]
	v_mfma_f32_16x16x32_bf16 v[0:3], v[168:171], v[184:187], v[0:3]
	v_mfma_f32_16x16x32_bf16 v[116:119], v[160:163], v[192:195], v[116:119]
	v_mfma_f32_16x16x32_bf16 v[112:115], v[168:171], v[192:195], v[112:115]
	v_mfma_f32_16x16x32_bf16 v[108:111], v[160:163], v[200:203], v[108:111]
	v_mfma_f32_16x16x32_bf16 v[100:103], v[168:171], v[200:203], v[100:103]
	v_mfma_f32_16x16x32_bf16 v[36:39], v[164:167], v[180:183], v[36:39]
	v_mfma_f32_16x16x32_bf16 v[4:7], v[172:175], v[180:183], v[4:7]
	v_mfma_f32_16x16x32_bf16 v[32:35], v[164:167], v[188:191], v[32:35]
	v_mfma_f32_16x16x32_bf16 v[0:3], v[172:175], v[188:191], v[0:3]
	v_mfma_f32_16x16x32_bf16 v[116:119], v[164:167], v[196:199], v[116:119]
	v_mfma_f32_16x16x32_bf16 v[112:115], v[172:175], v[196:199], v[112:115]
	v_mfma_f32_16x16x32_bf16 v[108:111], v[164:167], v[204:207], v[108:111]
	v_mfma_f32_16x16x32_bf16 v[100:103], v[172:175], v[204:207], v[100:103]
	s_barrier
	s_add_i32 s62, 0, 0x18000
	s_add_i32 s63, 0, 0x1c000
	v_add_u32_e32 v156, s62, v235
	v_add_u32_e32 v172, s63, v235
	ds_read_b128 v[120:123], v156
	ds_read_b128 v[124:127], v156 offset:1024
	ds_read_b128 v[152:155], v156 offset:2048
	ds_read_b128 v[156:159], v156 offset:3072
	ds_read_b128 v[160:163], v172
	ds_read_b128 v[164:167], v172 offset:1024
	ds_read_b128 v[168:171], v172 offset:2048
	ds_read_b128 v[172:175], v172 offset:3072
	s_add_u32 s26, s68, 0x2000
	s_addc_u32 s27, s69, 0
	s_mov_b32 m0, s73
	v_lshl_add_u64 v[216:217], s[26:27], 0, v[136:137]
	ds_read_b128 v[176:179], v240 offset:32768
	ds_read_b128 v[180:183], v240 offset:33792
	ds_read_b128 v[184:187], v240 offset:34816
	ds_read_b128 v[188:191], v240 offset:35840
	ds_read_b128 v[192:195], v240 offset:36864
	ds_read_b128 v[196:199], v240 offset:37888
	ds_read_b128 v[200:203], v240 offset:38912
	ds_read_b128 v[204:207], v240 offset:39936
	global_load_lds_dwordx4 v[216:217], off
	v_lshl_add_u64 v[216:217], s[26:27], 0, v[140:141]
	s_mov_b32 m0, s74
	s_nop 0
	global_load_lds_dwordx4 v[216:217], off
	s_waitcnt vmcnt(8)
	s_waitcnt lgkmcnt(0)
	s_barrier
	s_waitcnt lgkmcnt(0)
	v_mfma_f32_16x16x32_bf16 v[104:107], v[120:123], v[176:179], v[104:107]
	v_mfma_f32_16x16x32_bf16 v[96:99], v[152:155], v[176:179], v[96:99]
	v_mfma_f32_16x16x32_bf16 v[92:95], v[120:123], v[184:187], v[92:95]
	v_mfma_f32_16x16x32_bf16 v[88:91], v[152:155], v[184:187], v[88:91]
	v_mfma_f32_16x16x32_bf16 v[60:63], v[120:123], v[192:195], v[60:63]
	v_mfma_f32_16x16x32_bf16 v[28:31], v[152:155], v[192:195], v[28:31]
	v_mfma_f32_16x16x32_bf16 v[56:59], v[120:123], v[200:203], v[56:59]
	v_mfma_f32_16x16x32_bf16 v[24:27], v[152:155], v[200:203], v[24:27]
	v_mfma_f32_16x16x32_bf16 v[104:107], v[124:127], v[180:183], v[104:107]
	v_mfma_f32_16x16x32_bf16 v[96:99], v[156:159], v[180:183], v[96:99]
	v_mfma_f32_16x16x32_bf16 v[92:95], v[124:127], v[188:191], v[92:95]
	v_mfma_f32_16x16x32_bf16 v[88:91], v[156:159], v[188:191], v[88:91]
	v_mfma_f32_16x16x32_bf16 v[60:63], v[124:127], v[196:199], v[60:63]
	v_mfma_f32_16x16x32_bf16 v[28:31], v[156:159], v[196:199], v[28:31]
	v_mfma_f32_16x16x32_bf16 v[56:59], v[124:127], v[204:207], v[56:59]
	v_mfma_f32_16x16x32_bf16 v[24:27], v[156:159], v[204:207], v[24:27]
	v_mfma_f32_16x16x32_bf16 v[84:87], v[160:163], v[176:179], v[84:87]
	v_mfma_f32_16x16x32_bf16 v[80:83], v[168:171], v[176:179], v[80:83]
	v_mfma_f32_16x16x32_bf16 v[76:79], v[160:163], v[184:187], v[76:79]
	v_mfma_f32_16x16x32_bf16 v[72:75], v[168:171], v[184:187], v[72:75]
	v_mfma_f32_16x16x32_bf16 v[48:51], v[160:163], v[192:195], v[48:51]
	v_mfma_f32_16x16x32_bf16 v[16:19], v[168:171], v[192:195], v[16:19]
	v_mfma_f32_16x16x32_bf16 v[40:43], v[160:163], v[200:203], v[40:43]
	v_mfma_f32_16x16x32_bf16 v[8:11], v[168:171], v[200:203], v[8:11]
	v_mfma_f32_16x16x32_bf16 v[84:87], v[164:167], v[180:183], v[84:87]
	v_mfma_f32_16x16x32_bf16 v[80:83], v[172:175], v[180:183], v[80:83]
	v_mfma_f32_16x16x32_bf16 v[76:79], v[164:167], v[188:191], v[76:79]
	v_mfma_f32_16x16x32_bf16 v[72:75], v[172:175], v[188:191], v[72:75]
	v_mfma_f32_16x16x32_bf16 v[48:51], v[164:167], v[196:199], v[48:51]
	v_mfma_f32_16x16x32_bf16 v[16:19], v[172:175], v[196:199], v[16:19]
	v_mfma_f32_16x16x32_bf16 v[40:43], v[164:167], v[204:207], v[40:43]
	v_mfma_f32_16x16x32_bf16 v[8:11], v[172:175], v[204:207], v[8:11]
	s_barrier
	s_add_i32 s26, s62, s70
	v_lshl_add_u64 v[208:209], v[208:209], 0, s[10:11]
	s_mov_b32 m0, s26
	ds_read_b128 v[176:179], v240 offset:49152
	ds_read_b128 v[180:183], v240 offset:50176
	ds_read_b128 v[184:187], v240 offset:51200
	ds_read_b128 v[188:191], v240 offset:52224
	ds_read_b128 v[192:195], v240 offset:53248
	ds_read_b128 v[196:199], v240 offset:54272
	ds_read_b128 v[200:203], v240 offset:55296
	ds_read_b128 v[204:207], v240 offset:56320
	global_load_lds_dwordx4 v[208:209], off
	s_add_i32 m0, s26, 0x2000
	s_add_u32 s26, s66, 0x40080
	v_lshl_add_u64 v[208:209], v[210:211], 0, s[10:11]
	s_addc_u32 s27, s67, 0
	s_add_i32 s62, s63, s70
	global_load_lds_dwordx4 v[208:209], off
	v_lshl_add_u64 v[208:209], s[26:27], 0, v[138:139]
	s_mov_b32 m0, s62
	s_nop 0
	global_load_lds_dwordx4 v[208:209], off
	v_lshl_add_u64 v[208:209], s[26:27], 0, v[142:143]
	s_add_i32 m0, s62, 0x2000
	s_nop 0
	global_load_lds_dwordx4 v[208:209], off
	v_lshl_add_u64 v[208:209], v[212:213], 0, s[10:11]
	s_mov_b32 m0, s78
	s_nop 0
	global_load_lds_dwordx4 v[208:209], off
	v_lshl_add_u64 v[208:209], v[214:215], 0, s[10:11]
	s_mov_b32 m0, s79
	s_nop 0
	global_load_lds_dwordx4 v[208:209], off
	s_waitcnt vmcnt(8)
	s_waitcnt lgkmcnt(0)
	s_barrier
	s_waitcnt lgkmcnt(0)
	v_mfma_f32_16x16x32_bf16 v[52:55], v[120:123], v[176:179], v[52:55]
	v_mfma_f32_16x16x32_bf16 v[44:47], v[120:123], v[184:187], v[44:47]
	v_mfma_f32_16x16x32_bf16 v[132:135], v[120:123], v[192:195], v[132:135]
	v_mfma_f32_16x16x32_bf16 v[64:67], v[120:123], v[200:203], v[64:67]
	v_mfma_f32_16x16x32_bf16 v[52:55], v[124:127], v[180:183], v[52:55]
	v_mfma_f32_16x16x32_bf16 v[20:23], v[152:155], v[176:179], v[20:23]
	v_mfma_f32_16x16x32_bf16 v[44:47], v[124:127], v[188:191], v[44:47]
	v_mfma_f32_16x16x32_bf16 v[12:15], v[152:155], v[184:187], v[12:15]
	v_mfma_f32_16x16x32_bf16 v[132:135], v[124:127], v[196:199], v[132:135]
	v_mfma_f32_16x16x32_bf16 v[128:131], v[152:155], v[192:195], v[128:131]
	v_mfma_f32_16x16x32_bf16 v[124:127], v[124:127], v[204:207], v[64:67]
	v_mfma_f32_16x16x32_bf16 v[64:67], v[152:155], v[200:203], v[68:71]
	v_mfma_f32_16x16x32_bf16 v[20:23], v[156:159], v[180:183], v[20:23]
	v_mfma_f32_16x16x32_bf16 v[12:15], v[156:159], v[188:191], v[12:15]
	v_mfma_f32_16x16x32_bf16 v[128:131], v[156:159], v[196:199], v[128:131]
	v_mfma_f32_16x16x32_bf16 v[120:123], v[156:159], v[204:207], v[64:67]
	v_mfma_f32_16x16x32_bf16 v[64:67], v[160:163], v[192:195], v[116:119]
	v_mfma_f32_16x16x32_bf16 v[116:119], v[164:167], v[196:199], v[64:67]
	v_mfma_f32_16x16x32_bf16 v[64:67], v[168:171], v[192:195], v[112:115]
	v_mfma_f32_16x16x32_bf16 v[112:115], v[172:175], v[196:199], v[64:67]
	v_mfma_f32_16x16x32_bf16 v[64:67], v[160:163], v[200:203], v[108:111]
	v_mfma_f32_16x16x32_bf16 v[36:39], v[160:163], v[176:179], v[36:39]
	v_mfma_f32_16x16x32_bf16 v[4:7], v[168:171], v[176:179], v[4:7]
	v_mfma_f32_16x16x32_bf16 v[32:35], v[160:163], v[184:187], v[32:35]
	v_mfma_f32_16x16x32_bf16 v[0:3], v[168:171], v[184:187], v[0:3]
	v_mfma_f32_16x16x32_bf16 v[108:111], v[164:167], v[204:207], v[64:67]
	v_mfma_f32_16x16x32_bf16 v[64:67], v[168:171], v[200:203], v[100:103]
	v_mfma_f32_16x16x32_bf16 v[36:39], v[164:167], v[180:183], v[36:39]
	v_mfma_f32_16x16x32_bf16 v[4:7], v[172:175], v[180:183], v[4:7]
	v_mfma_f32_16x16x32_bf16 v[32:35], v[164:167], v[188:191], v[32:35]
	v_mfma_f32_16x16x32_bf16 v[0:3], v[172:175], v[188:191], v[0:3]
	v_mfma_f32_16x16x32_bf16 v[100:103], v[172:175], v[204:207], v[64:67]
	s_barrier
	s_add_i32 s96, s96, 2
	s_add_u32 s94, s94, 0x100
	s_addc_u32 s95, s95, 0
	s_cmp_gt_u32 s96, 13
	s_mov_b64 s[62:63], s[64:65]
	s_cbranch_scc0 .LBB0_882
	s_and_b64 vcc, exec, s[18:19]
	s_cbranch_vccz .LBB0_885
	s_barrier

.LBB0_1067:
	ds_read_b128 v[140:143], v149
	ds_read_b128 v[152:155], v149 offset:1024
	ds_read_b128 v[156:159], v149 offset:2048
	ds_read_b128 v[160:163], v149 offset:3072
	ds_read_b128 v[164:167], v150
	ds_read_b128 v[168:171], v150 offset:1024
	ds_read_b128 v[172:175], v150 offset:2048
	ds_read_b128 v[176:179], v150 offset:3072
	s_add_u32 s36, s34, 0x100
	s_addc_u32 s37, s35, 0
	s_cmp_eq_u32 s57, 40
	s_cselect_b32 s41, s5, s37
	s_cselect_b32 s40, s4, s36
	s_cselect_b32 s39, s31, s56
	s_cselect_b32 s38, s30, s55
	v_lshl_add_u64 v[144:145], s[34:35], 0, v[132:133]
	s_add_i32 m0, s42, 0xc000
	ds_read_b128 v[180:183], v151
	ds_read_b128 v[184:187], v151 offset:1024
	ds_read_b128 v[188:191], v151 offset:2048
	ds_read_b128 v[192:195], v151 offset:3072
	ds_read_b128 v[196:199], v151 offset:4096
	ds_read_b128 v[200:203], v151 offset:5120
	ds_read_b128 v[204:207], v151 offset:6144
	ds_read_b128 v[208:211], v151 offset:7168
	global_load_lds_dwordx4 v[144:145], off
	v_lshl_add_u64 v[144:145], s[34:35], 0, v[134:135]
	s_add_i32 m0, s42, 0xe000
	s_nop 0
	global_load_lds_dwordx4 v[144:145], off
	s_waitcnt vmcnt(8)
	s_waitcnt lgkmcnt(0)
	s_barrier
	s_waitcnt lgkmcnt(0)
	v_mfma_f32_16x16x32_bf16 v[124:127], v[140:143], v[180:183], v[124:127]
	v_mfma_f32_16x16x32_bf16 v[120:123], v[156:159], v[180:183], v[120:123]
	v_mfma_f32_16x16x32_bf16 v[112:115], v[140:143], v[188:191], v[112:115]
	v_mfma_f32_16x16x32_bf16 v[104:107], v[156:159], v[188:191], v[104:107]
	v_mfma_f32_16x16x32_bf16 v[96:99], v[140:143], v[196:199], v[96:99]
	v_mfma_f32_16x16x32_bf16 v[88:91], v[156:159], v[196:199], v[88:91]
	v_mfma_f32_16x16x32_bf16 v[80:83], v[140:143], v[204:207], v[80:83]
	v_mfma_f32_16x16x32_bf16 v[72:75], v[156:159], v[204:207], v[72:75]
	v_mfma_f32_16x16x32_bf16 v[124:127], v[152:155], v[184:187], v[124:127]
	v_mfma_f32_16x16x32_bf16 v[120:123], v[160:163], v[184:187], v[120:123]
	v_mfma_f32_16x16x32_bf16 v[112:115], v[152:155], v[192:195], v[112:115]
	v_mfma_f32_16x16x32_bf16 v[104:107], v[160:163], v[192:195], v[104:107]
	v_mfma_f32_16x16x32_bf16 v[96:99], v[152:155], v[200:203], v[96:99]
	v_mfma_f32_16x16x32_bf16 v[88:91], v[160:163], v[200:203], v[88:91]
	v_mfma_f32_16x16x32_bf16 v[80:83], v[152:155], v[208:211], v[80:83]
	v_mfma_f32_16x16x32_bf16 v[72:75], v[160:163], v[208:211], v[72:75]
	v_mfma_f32_16x16x32_bf16 v[116:119], v[164:167], v[180:183], v[116:119]
	v_mfma_f32_16x16x32_bf16 v[108:111], v[172:175], v[180:183], v[108:111]
	v_mfma_f32_16x16x32_bf16 v[100:103], v[164:167], v[188:191], v[100:103]
	v_mfma_f32_16x16x32_bf16 v[92:95], v[172:175], v[188:191], v[92:95]
	v_mfma_f32_16x16x32_bf16 v[84:87], v[164:167], v[196:199], v[84:87]
	v_mfma_f32_16x16x32_bf16 v[76:79], v[172:175], v[196:199], v[76:79]
	v_mfma_f32_16x16x32_bf16 v[68:71], v[164:167], v[204:207], v[68:71]
	v_mfma_f32_16x16x32_bf16 v[64:67], v[172:175], v[204:207], v[64:67]
	v_mfma_f32_16x16x32_bf16 v[116:119], v[168:171], v[184:187], v[116:119]
	v_mfma_f32_16x16x32_bf16 v[108:111], v[176:179], v[184:187], v[108:111]
	v_mfma_f32_16x16x32_bf16 v[100:103], v[168:171], v[192:195], v[100:103]
	v_mfma_f32_16x16x32_bf16 v[92:95], v[176:179], v[192:195], v[92:95]
	v_mfma_f32_16x16x32_bf16 v[84:87], v[168:171], v[200:203], v[84:87]
	v_mfma_f32_16x16x32_bf16 v[76:79], v[176:179], v[200:203], v[76:79]
	v_mfma_f32_16x16x32_bf16 v[68:71], v[168:171], v[208:211], v[68:71]
	v_mfma_f32_16x16x32_bf16 v[64:67], v[176:179], v[208:211], v[64:67]
	s_barrier
	s_add_i32 s26, s49, s33
	v_lshl_add_u64 v[144:145], s[38:39], 0, v[128:129]
	s_mov_b32 m0, s26
	ds_read_b128 v[180:183], v151 offset:16384
	ds_read_b128 v[184:187], v151 offset:17408
	ds_read_b128 v[188:191], v151 offset:18432
	ds_read_b128 v[192:195], v151 offset:19456
	ds_read_b128 v[196:199], v151 offset:20480
	ds_read_b128 v[200:203], v151 offset:21504
	ds_read_b128 v[204:207], v151 offset:22528
	ds_read_b128 v[208:211], v151 offset:23552
	global_load_lds_dwordx4 v[144:145], off
	s_add_i32 m0, s26, 0x2000
	s_add_u32 s26, s38, 0xb0000
	v_lshl_add_u64 v[212:213], s[38:39], 0, v[130:131]
	s_addc_u32 s27, s39, 0
	s_add_i32 s34, s50, s33
	global_load_lds_dwordx4 v[212:213], off
	v_lshl_add_u64 v[214:215], s[26:27], 0, v[128:129]
	s_mov_b32 m0, s34
	v_lshl_add_u64 v[216:217], s[40:41], 0, v[130:131]
	global_load_lds_dwordx4 v[214:215], off
	v_lshl_add_u64 v[214:215], s[26:27], 0, v[130:131]
	s_add_i32 m0, s34, 0x2000
	s_nop 0
	global_load_lds_dwordx4 v[214:215], off
	v_lshl_add_u64 v[214:215], s[40:41], 0, v[128:129]
	s_mov_b32 m0, s42
	s_nop 0
	global_load_lds_dwordx4 v[214:215], off
	s_mov_b32 m0, s43
	s_nop 0
	global_load_lds_dwordx4 v[216:217], off
	s_waitcnt vmcnt(8)
	s_waitcnt lgkmcnt(0)
	s_barrier
	s_waitcnt lgkmcnt(0)
	v_mfma_f32_16x16x32_bf16 v[60:63], v[140:143], v[180:183], v[60:63]
	v_mfma_f32_16x16x32_bf16 v[56:59], v[156:159], v[180:183], v[56:59]
	v_mfma_f32_16x16x32_bf16 v[48:51], v[140:143], v[188:191], v[48:51]
	v_mfma_f32_16x16x32_bf16 v[40:43], v[156:159], v[188:191], v[40:43]
	v_mfma_f32_16x16x32_bf16 v[32:35], v[140:143], v[196:199], v[32:35]
	v_mfma_f32_16x16x32_bf16 v[24:27], v[156:159], v[196:199], v[24:27]
	v_mfma_f32_16x16x32_bf16 v[16:19], v[140:143], v[204:207], v[16:19]
	v_mfma_f32_16x16x32_bf16 v[8:11], v[156:159], v[204:207], v[8:11]
	v_mfma_f32_16x16x32_bf16 v[60:63], v[152:155], v[184:187], v[60:63]
	v_mfma_f32_16x16x32_bf16 v[56:59], v[160:163], v[184:187], v[56:59]
	v_mfma_f32_16x16x32_bf16 v[48:51], v[152:155], v[192:195], v[48:51]
	v_mfma_f32_16x16x32_bf16 v[40:43], v[160:163], v[192:195], v[40:43]
	v_mfma_f32_16x16x32_bf16 v[32:35], v[152:155], v[200:203], v[32:35]
	v_mfma_f32_16x16x32_bf16 v[24:27], v[160:163], v[200:203], v[24:27]
	v_mfma_f32_16x16x32_bf16 v[16:19], v[152:155], v[208:211], v[16:19]
	v_mfma_f32_16x16x32_bf16 v[8:11], v[160:163], v[208:211], v[8:11]
	v_mfma_f32_16x16x32_bf16 v[52:55], v[164:167], v[180:183], v[52:55]
	v_mfma_f32_16x16x32_bf16 v[44:47], v[172:175], v[180:183], v[44:47]
	v_mfma_f32_16x16x32_bf16 v[36:39], v[164:167], v[188:191], v[36:39]
	v_mfma_f32_16x16x32_bf16 v[28:31], v[172:175], v[188:191], v[28:31]
	v_mfma_f32_16x16x32_bf16 v[20:23], v[164:167], v[196:199], v[20:23]
	v_mfma_f32_16x16x32_bf16 v[12:15], v[172:175], v[196:199], v[12:15]
	v_mfma_f32_16x16x32_bf16 v[4:7], v[164:167], v[204:207], v[4:7]
	v_mfma_f32_16x16x32_bf16 v[0:3], v[172:175], v[204:207], v[0:3]
	v_mfma_f32_16x16x32_bf16 v[52:55], v[168:171], v[184:187], v[52:55]
	v_mfma_f32_16x16x32_bf16 v[44:47], v[176:179], v[184:187], v[44:47]
	v_mfma_f32_16x16x32_bf16 v[36:39], v[168:171], v[192:195], v[36:39]
	v_mfma_f32_16x16x32_bf16 v[28:31], v[176:179], v[192:195], v[28:31]
	v_mfma_f32_16x16x32_bf16 v[20:23], v[168:171], v[200:203], v[20:23]
	v_mfma_f32_16x16x32_bf16 v[12:15], v[176:179], v[200:203], v[12:15]
	v_mfma_f32_16x16x32_bf16 v[4:7], v[168:171], v[208:211], v[4:7]
	v_mfma_f32_16x16x32_bf16 v[0:3], v[176:179], v[208:211], v[0:3]
	s_barrier
	s_add_i32 s34, 0, 0x18000
	s_add_i32 s35, 0, 0x1c000
	v_add_u32_e32 v160, s34, v147
	v_add_u32_e32 v176, s35, v147
	ds_read_b128 v[140:143], v160
	ds_read_b128 v[152:155], v160 offset:1024
	ds_read_b128 v[156:159], v160 offset:2048
	ds_read_b128 v[160:163], v160 offset:3072
	ds_read_b128 v[164:167], v176
	ds_read_b128 v[168:171], v176 offset:1024
	ds_read_b128 v[172:175], v176 offset:2048
	ds_read_b128 v[176:179], v176 offset:3072
	s_add_u32 s26, s40, 0xb0000
	s_addc_u32 s27, s41, 0
	s_mov_b32 m0, s44
	v_lshl_add_u64 v[218:219], s[26:27], 0, v[128:129]
	ds_read_b128 v[180:183], v151 offset:32768
	ds_read_b128 v[184:187], v151 offset:33792
	ds_read_b128 v[188:191], v151 offset:34816
	ds_read_b128 v[192:195], v151 offset:35840
	ds_read_b128 v[196:199], v151 offset:36864
	ds_read_b128 v[200:203], v151 offset:37888
	ds_read_b128 v[204:207], v151 offset:38912
	ds_read_b128 v[208:211], v151 offset:39936
	global_load_lds_dwordx4 v[218:219], off
	v_lshl_add_u64 v[218:219], s[26:27], 0, v[130:131]
	s_mov_b32 m0, s45
	s_nop 0
	global_load_lds_dwordx4 v[218:219], off
	s_waitcnt vmcnt(8)
	s_waitcnt lgkmcnt(0)
	s_barrier
	s_waitcnt lgkmcnt(0)
	v_mfma_f32_16x16x32_bf16 v[124:127], v[140:143], v[180:183], v[124:127]
	v_mfma_f32_16x16x32_bf16 v[120:123], v[156:159], v[180:183], v[120:123]
	v_mfma_f32_16x16x32_bf16 v[112:115], v[140:143], v[188:191], v[112:115]
	v_mfma_f32_16x16x32_bf16 v[104:107], v[156:159], v[188:191], v[104:107]
	v_mfma_f32_16x16x32_bf16 v[96:99], v[140:143], v[196:199], v[96:99]
	v_mfma_f32_16x16x32_bf16 v[88:91], v[156:159], v[196:199], v[88:91]
	v_mfma_f32_16x16x32_bf16 v[80:83], v[140:143], v[204:207], v[80:83]
	v_mfma_f32_16x16x32_bf16 v[72:75], v[156:159], v[204:207], v[72:75]
	v_mfma_f32_16x16x32_bf16 v[124:127], v[152:155], v[184:187], v[124:127]
	v_mfma_f32_16x16x32_bf16 v[120:123], v[160:163], v[184:187], v[120:123]
	v_mfma_f32_16x16x32_bf16 v[112:115], v[152:155], v[192:195], v[112:115]
	v_mfma_f32_16x16x32_bf16 v[104:107], v[160:163], v[192:195], v[104:107]
	v_mfma_f32_16x16x32_bf16 v[96:99], v[152:155], v[200:203], v[96:99]
	v_mfma_f32_16x16x32_bf16 v[88:91], v[160:163], v[200:203], v[88:91]
	v_mfma_f32_16x16x32_bf16 v[80:83], v[152:155], v[208:211], v[80:83]
	v_mfma_f32_16x16x32_bf16 v[72:75], v[160:163], v[208:211], v[72:75]
	v_mfma_f32_16x16x32_bf16 v[116:119], v[164:167], v[180:183], v[116:119]
	v_mfma_f32_16x16x32_bf16 v[108:111], v[172:175], v[180:183], v[108:111]
	v_mfma_f32_16x16x32_bf16 v[100:103], v[164:167], v[188:191], v[100:103]
	v_mfma_f32_16x16x32_bf16 v[92:95], v[172:175], v[188:191], v[92:95]
	v_mfma_f32_16x16x32_bf16 v[84:87], v[164:167], v[196:199], v[84:87]
	v_mfma_f32_16x16x32_bf16 v[76:79], v[172:175], v[196:199], v[76:79]
	v_mfma_f32_16x16x32_bf16 v[68:71], v[164:167], v[204:207], v[68:71]
	v_mfma_f32_16x16x32_bf16 v[64:67], v[172:175], v[204:207], v[64:67]
	v_mfma_f32_16x16x32_bf16 v[116:119], v[168:171], v[184:187], v[116:119]
	v_mfma_f32_16x16x32_bf16 v[108:111], v[176:179], v[184:187], v[108:111]
	v_mfma_f32_16x16x32_bf16 v[100:103], v[168:171], v[192:195], v[100:103]
	v_mfma_f32_16x16x32_bf16 v[92:95], v[176:179], v[192:195], v[92:95]
	v_mfma_f32_16x16x32_bf16 v[84:87], v[168:171], v[200:203], v[84:87]
	v_mfma_f32_16x16x32_bf16 v[76:79], v[176:179], v[200:203], v[76:79]
	v_mfma_f32_16x16x32_bf16 v[68:71], v[168:171], v[208:211], v[68:71]
	v_mfma_f32_16x16x32_bf16 v[64:67], v[176:179], v[208:211], v[64:67]
	s_barrier
	s_add_i32 s26, s34, s33
	v_lshl_add_u64 v[144:145], v[144:145], 0, s[8:9]
	s_mov_b32 m0, s26
	ds_read_b128 v[180:183], v151 offset:49152
	ds_read_b128 v[184:187], v151 offset:50176
	ds_read_b128 v[188:191], v151 offset:51200
	ds_read_b128 v[192:195], v151 offset:52224
	ds_read_b128 v[196:199], v151 offset:53248
	ds_read_b128 v[200:203], v151 offset:54272
	ds_read_b128 v[204:207], v151 offset:55296
	ds_read_b128 v[208:211], v151 offset:56320
	global_load_lds_dwordx4 v[144:145], off
	s_add_i32 m0, s26, 0x2000
	s_add_u32 s26, s38, 0xb0080
	v_lshl_add_u64 v[144:145], v[212:213], 0, s[8:9]
	s_addc_u32 s27, s39, 0
	s_add_i32 s34, s35, s33
	global_load_lds_dwordx4 v[144:145], off
	v_lshl_add_u64 v[144:145], s[26:27], 0, v[128:129]
	s_mov_b32 m0, s34
	s_nop 0
	global_load_lds_dwordx4 v[144:145], off
	v_lshl_add_u64 v[144:145], s[26:27], 0, v[130:131]
	s_add_i32 m0, s34, 0x2000
	s_nop 0
	global_load_lds_dwordx4 v[144:145], off
	v_lshl_add_u64 v[144:145], v[214:215], 0, s[8:9]
	s_mov_b32 m0, s47
	s_nop 0
	global_load_lds_dwordx4 v[144:145], off
	v_lshl_add_u64 v[144:145], v[216:217], 0, s[8:9]
	s_mov_b32 m0, s48
	s_nop 0
	global_load_lds_dwordx4 v[144:145], off
	s_waitcnt vmcnt(8)
	s_waitcnt lgkmcnt(0)
	s_barrier
	s_waitcnt lgkmcnt(0)
	v_mfma_f32_16x16x32_bf16 v[60:63], v[140:143], v[180:183], v[60:63]
	v_mfma_f32_16x16x32_bf16 v[56:59], v[156:159], v[180:183], v[56:59]
	v_mfma_f32_16x16x32_bf16 v[48:51], v[140:143], v[188:191], v[48:51]
	v_mfma_f32_16x16x32_bf16 v[40:43], v[156:159], v[188:191], v[40:43]
	v_mfma_f32_16x16x32_bf16 v[32:35], v[140:143], v[196:199], v[32:35]
	v_mfma_f32_16x16x32_bf16 v[24:27], v[156:159], v[196:199], v[24:27]
	v_mfma_f32_16x16x32_bf16 v[16:19], v[140:143], v[204:207], v[16:19]
	v_mfma_f32_16x16x32_bf16 v[8:11], v[156:159], v[204:207], v[8:11]
	v_mfma_f32_16x16x32_bf16 v[60:63], v[152:155], v[184:187], v[60:63]
	v_mfma_f32_16x16x32_bf16 v[56:59], v[160:163], v[184:187], v[56:59]
	v_mfma_f32_16x16x32_bf16 v[48:51], v[152:155], v[192:195], v[48:51]
	v_mfma_f32_16x16x32_bf16 v[40:43], v[160:163], v[192:195], v[40:43]
	v_mfma_f32_16x16x32_bf16 v[32:35], v[152:155], v[200:203], v[32:35]
	v_mfma_f32_16x16x32_bf16 v[24:27], v[160:163], v[200:203], v[24:27]
	v_mfma_f32_16x16x32_bf16 v[16:19], v[152:155], v[208:211], v[16:19]
	v_mfma_f32_16x16x32_bf16 v[8:11], v[160:163], v[208:211], v[8:11]
	v_mfma_f32_16x16x32_bf16 v[52:55], v[164:167], v[180:183], v[52:55]
	v_mfma_f32_16x16x32_bf16 v[44:47], v[172:175], v[180:183], v[44:47]
	v_mfma_f32_16x16x32_bf16 v[36:39], v[164:167], v[188:191], v[36:39]
	v_mfma_f32_16x16x32_bf16 v[28:31], v[172:175], v[188:191], v[28:31]
	v_mfma_f32_16x16x32_bf16 v[20:23], v[164:167], v[196:199], v[20:23]
	v_mfma_f32_16x16x32_bf16 v[12:15], v[172:175], v[196:199], v[12:15]
	v_mfma_f32_16x16x32_bf16 v[4:7], v[164:167], v[204:207], v[4:7]
	v_mfma_f32_16x16x32_bf16 v[0:3], v[172:175], v[204:207], v[0:3]
	v_mfma_f32_16x16x32_bf16 v[52:55], v[168:171], v[184:187], v[52:55]
	v_mfma_f32_16x16x32_bf16 v[44:47], v[176:179], v[184:187], v[44:47]
	v_mfma_f32_16x16x32_bf16 v[36:39], v[168:171], v[192:195], v[36:39]
	v_mfma_f32_16x16x32_bf16 v[28:31], v[176:179], v[192:195], v[28:31]
	v_mfma_f32_16x16x32_bf16 v[20:23], v[168:171], v[200:203], v[20:23]
	v_mfma_f32_16x16x32_bf16 v[12:15], v[176:179], v[200:203], v[12:15]
	v_mfma_f32_16x16x32_bf16 v[4:7], v[168:171], v[208:211], v[4:7]
	v_mfma_f32_16x16x32_bf16 v[0:3], v[176:179], v[208:211], v[0:3]
	s_barrier
	s_add_i32 s57, s57, 2
	s_add_u32 s55, s55, 0x100
	s_addc_u32 s56, s56, 0
	s_cmp_gt_u32 s57, 41
	s_mov_b64 s[34:35], s[36:37]
	s_cbranch_scc0 .LBB0_1067
	s_and_b64 vcc, exec, s[10:11]
	s_cbranch_vccz .LBB0_1070
	s_barrier
